# GEMM compute segments: snake issue order of the 8-MFMA groups (consecutive MFMAs share one input fragment)
# speedup vs baseline: 1.0031x; 1.0031x over previous
; #define PG8_STAGE(bufoff, gbase, voff) do { _Pragma("unroll") for (int _i = 0; _i < 2; ++_i) \
;         __builtin_amdgcn_global_load_lds((const unsigned*)((const char*)(gbase) + (voff)[_i]), (PG8_LAS unsigned*)(lds + (bufoff) + ldsw + _i * 8192), 16, 0, 0); } while (0)
; #define PG8_LDA(dst, b, h) do { _Pragma("unroll") for (int m = 0; m < 4; ++m) _Pragma("unroll") for (int k = 0; k < 2; ++k) dst[m][k] = *(const PG8_LAS bf16x8*)(lds + PG8_SA(b, h) + aoff + m * 2048 + k * 1024); } while (0)
; #define PG8_LDB(dst, b, h) do { _Pragma("unroll") for (int n = 0; n < 2; ++n) _Pragma("unroll") for (int k = 0; k < 2; ++k) dst[n][k] = *(const PG8_LAS bf16x8*)(lds + PG8_SB(b, h) + boff + n * 2048 + k * 1024); } while (0)
; template <class Epi, class Sched, bool ALIGN_EPI = false, bool SP2 = false>
; __device__ __forceinline__ void gemm_phase(PG8_LAS unsigned char* lds, const Gemm g, const Sched& S, const Epi& E) {
;     ...
;         for (int t = 0; t < nt; t += 2) {
;             const bool last = (t == nt - 2);
;             const char* a1 = cA + (size_t)(t + 1) * kstep;
;             const char* a2 = last ? nA : cA + (size_t)(t + 2) * kstep; const char* b2 = last ? nB : cB + (size_t)(t + 2) * kstep;
;             const char* a3 = a2 + kstep; const char* b3 = b2 + kstep;
;             if (last && has_next) S.a_ready(nxt);
;             if constexpr (SP2) {
;             PG8_LDB(B0, 0, 0); PG8_LDB(B1, 0, 1); PG8_SCHED; PG8_LDA(At, 0, 0); PG8_STAGE(PG8_SA(1, 1), a1 + hstep, voffA);
;             PG8_WAIT_V(8); PG8_WAIT_L(0); PG8_BAR; PG8_MMA(0, 0, At, B0); PG8_MMA(0, 1, At, B1); PG8_BAR; PG8_SCHED;
;             PG8_LDA(At, 0, 1); PG8_STAGE(PG8_SB(0, 0), b2, voffB); PG8_STAGE(PG8_SB(0, 1), b2 + hstep, voffB); PG8_STAGE(PG8_SA(0, 0), a2, voffA);
;             PG8_WAIT_V(8); PG8_WAIT_L(0); PG8_BAR; PG8_MMA(1, 0, At, B0); PG8_MMA(1, 1, At, B1); PG8_BAR; PG8_SCHED;
;             PG8_LDB(B0, 1, 0); PG8_LDB(B1, 1, 1); PG8_SCHED; PG8_LDA(At, 1, 0); PG8_STAGE(PG8_SA(0, 1), a2 + hstep, voffA);
;             PG8_WAIT_V(8); PG8_WAIT_L(0); PG8_BAR; PG8_MMA(0, 0, At, B0); PG8_MMA(0, 1, At, B1); PG8_BAR; PG8_SCHED;
;             PG8_LDA(At, 1, 1); PG8_STAGE(PG8_SB(1, 0), b3, voffB); PG8_STAGE(PG8_SB(1, 1), b3 + hstep, voffB); PG8_STAGE(PG8_SA(1, 0), a3, voffA);
;             PG8_WAIT_V(8); PG8_WAIT_L(0); PG8_BAR; PG8_MMA(1, 0, At, B0); PG8_MMA(1, 1, At, B1); PG8_BAR; PG8_SCHED;
.LBB0_310:
	s_add_u32 s20, s44, 0xfff80080
	s_addc_u32 s21, s45, -1
	s_add_i32 s30, 0, 0x10000
	s_cmp_eq_u32 s56, 28
	s_cselect_b32 s47, s27, s21
	s_cselect_b32 s46, s52, s20
	v_add_u32_e32 v149, s30, v146
	s_cselect_b32 s21, s25, s55
	s_cselect_b32 s20, s53, s54
	s_add_i32 s57, 0, 0x14000
	ds_read_b128 v[142:145], v149
	ds_read_b128 v[150:153], v149 offset:1024
	ds_read_b128 v[154:157], v149 offset:2048
	ds_read_b128 v[158:161], v149 offset:3072
	v_add_u32_e32 v149, s57, v146
	ds_read_b128 v[162:165], v149
	ds_read_b128 v[166:169], v149 offset:1024
	ds_read_b128 v[170:173], v149 offset:2048
	ds_read_b128 v[174:177], v149 offset:3072
	v_lshl_add_u64 v[210:211], s[44:45], 0, v[140:141]
	s_add_i32 m0, s12, 0xc000
	ds_read_b128 v[178:181], v148
	ds_read_b128 v[182:185], v148 offset:1024
	ds_read_b128 v[186:189], v148 offset:2048
	ds_read_b128 v[190:193], v148 offset:3072
	ds_read_b128 v[194:197], v148 offset:4096
	ds_read_b128 v[198:201], v148 offset:5120
	ds_read_b128 v[202:205], v148 offset:6144
	ds_read_b128 v[206:209], v148 offset:7168
	global_load_lds_dwordx4 v[210:211], off
	v_lshl_add_u64 v[210:211], s[44:45], 0, v[138:139]
	s_add_i32 m0, s12, 0xe000
	s_nop 0
	global_load_lds_dwordx4 v[210:211], off
	s_waitcnt vmcnt(8)
	s_waitcnt lgkmcnt(0)
	s_barrier
	s_setprio 1
	s_waitcnt lgkmcnt(0)
	v_mfma_f32_16x16x32_bf16 v[128:131], v[142:145], v[178:181], v[128:131]
	v_mfma_f32_16x16x32_bf16 v[124:127], v[154:157], v[178:181], v[124:127]
	v_mfma_f32_16x16x32_bf16 v[112:115], v[154:157], v[186:189], v[112:115]
	v_mfma_f32_16x16x32_bf16 v[120:123], v[142:145], v[186:189], v[120:123]
	v_mfma_f32_16x16x32_bf16 v[104:107], v[142:145], v[194:197], v[104:107]
	v_mfma_f32_16x16x32_bf16 v[96:99], v[154:157], v[194:197], v[96:99]
	v_mfma_f32_16x16x32_bf16 v[80:83], v[154:157], v[202:205], v[80:83]
	v_mfma_f32_16x16x32_bf16 v[88:91], v[142:145], v[202:205], v[88:91]
	v_mfma_f32_16x16x32_bf16 v[128:131], v[150:153], v[182:185], v[128:131]
	v_mfma_f32_16x16x32_bf16 v[124:127], v[158:161], v[182:185], v[124:127]
	v_mfma_f32_16x16x32_bf16 v[112:115], v[158:161], v[190:193], v[112:115]
	v_mfma_f32_16x16x32_bf16 v[120:123], v[150:153], v[190:193], v[120:123]
	v_mfma_f32_16x16x32_bf16 v[104:107], v[150:153], v[198:201], v[104:107]
	v_mfma_f32_16x16x32_bf16 v[96:99], v[158:161], v[198:201], v[96:99]
	v_mfma_f32_16x16x32_bf16 v[80:83], v[158:161], v[206:209], v[80:83]
	v_mfma_f32_16x16x32_bf16 v[88:91], v[150:153], v[206:209], v[88:91]
	s_setprio 0
	s_setprio 1
	v_mfma_f32_16x16x32_bf16 v[116:119], v[162:165], v[178:181], v[116:119]
	v_mfma_f32_16x16x32_bf16 v[108:111], v[170:173], v[178:181], v[108:111]
	v_mfma_f32_16x16x32_bf16 v[92:95], v[170:173], v[186:189], v[92:95]
	v_mfma_f32_16x16x32_bf16 v[100:103], v[162:165], v[186:189], v[100:103]
	v_mfma_f32_16x16x32_bf16 v[84:87], v[162:165], v[194:197], v[84:87]
	v_mfma_f32_16x16x32_bf16 v[76:79], v[170:173], v[194:197], v[76:79]
	v_mfma_f32_16x16x32_bf16 v[68:71], v[170:173], v[202:205], v[68:71]
	v_mfma_f32_16x16x32_bf16 v[72:75], v[162:165], v[202:205], v[72:75]
	v_mfma_f32_16x16x32_bf16 v[116:119], v[166:169], v[182:185], v[116:119]
	v_mfma_f32_16x16x32_bf16 v[108:111], v[174:177], v[182:185], v[108:111]
	v_mfma_f32_16x16x32_bf16 v[92:95], v[174:177], v[190:193], v[92:95]
	v_mfma_f32_16x16x32_bf16 v[100:103], v[166:169], v[190:193], v[100:103]
	v_mfma_f32_16x16x32_bf16 v[84:87], v[166:169], v[198:201], v[84:87]
	v_mfma_f32_16x16x32_bf16 v[76:79], v[174:177], v[198:201], v[76:79]
	v_mfma_f32_16x16x32_bf16 v[68:71], v[174:177], v[206:209], v[68:71]
	v_mfma_f32_16x16x32_bf16 v[72:75], v[166:169], v[206:209], v[72:75]
	s_setprio 0
	s_barrier
	s_add_i32 s30, s30, s10
	v_lshl_add_u64 v[210:211], s[20:21], 0, v[2:3]
	s_mov_b32 m0, s30
	ds_read_b128 v[178:181], v148 offset:16384
	ds_read_b128 v[182:185], v148 offset:17408
	ds_read_b128 v[186:189], v148 offset:18432
	ds_read_b128 v[190:193], v148 offset:19456
	ds_read_b128 v[194:197], v148 offset:20480
	ds_read_b128 v[198:201], v148 offset:21504
	ds_read_b128 v[202:205], v148 offset:22528
	ds_read_b128 v[206:209], v148 offset:23552
	global_load_lds_dwordx4 v[210:211], off
	s_add_i32 m0, s30, 0x2000
	s_add_u32 s30, s20, 0x80000
	v_lshl_add_u64 v[212:213], s[20:21], 0, v[132:133]
	s_addc_u32 s31, s21, 0
	s_add_i32 s57, s57, s10
	global_load_lds_dwordx4 v[212:213], off
	v_lshl_add_u64 v[214:215], s[30:31], 0, v[2:3]
	s_mov_b32 m0, s57
	v_lshl_add_u64 v[216:217], s[46:47], 0, v[134:135]
	global_load_lds_dwordx4 v[214:215], off
	v_lshl_add_u64 v[214:215], s[30:31], 0, v[132:133]
	s_add_i32 m0, s57, 0x2000
	s_nop 0
	global_load_lds_dwordx4 v[214:215], off
	v_lshl_add_u64 v[214:215], s[46:47], 0, v[136:137]
	s_mov_b32 m0, s12
	s_nop 0
	global_load_lds_dwordx4 v[214:215], off
	s_mov_b32 m0, s13
	s_nop 0
	global_load_lds_dwordx4 v[216:217], off
	s_waitcnt vmcnt(8)
	s_waitcnt lgkmcnt(0)
	s_barrier
; #define PG8_STAGE(bufoff, gbase, voff) do { _Pragma("unroll") for (int _i = 0; _i < 2; ++_i) \
;         __builtin_amdgcn_global_load_lds((const unsigned*)((const char*)(gbase) + (voff)[_i]), (PG8_LAS unsigned*)(lds + (bufoff) + ldsw + _i * 8192), 16, 0, 0); } while (0)
; #define PG8_LDA(dst, b, h) do { _Pragma("unroll") for (int m = 0; m < 4; ++m) _Pragma("unroll") for (int k = 0; k < 2; ++k) dst[m][k] = *(const PG8_LAS bf16x8*)(lds + PG8_SA(b, h) + aoff + m * 2048 + k * 1024); } while (0)
; #define PG8_LDB(dst, b, h) do { _Pragma("unroll") for (int n = 0; n < 2; ++n) _Pragma("unroll") for (int k = 0; k < 2; ++k) dst[n][k] = *(const PG8_LAS bf16x8*)(lds + PG8_SB(b, h) + boff + n * 2048 + k * 1024); } while (0)
; #define PG8_MMA(ai, bj, At, Bt) do { __builtin_amdgcn_s_setprio(1); _Pragma("unroll") for (int m = 0; m < 4; ++m) _Pragma("unroll") for (int n = 0; n < 2; ++n) _Pragma("unroll") for (int k = 0; k < 2; ++k) \
;         acc[ai][bj][m][n] = __builtin_amdgcn_mfma_f32_16x16x32_bf16(Bt[n][k], At[m][k], acc[ai][bj][m][n], 0, 0, 0); __builtin_amdgcn_s_setprio(0); } while (0)
; #define PG8_WAIT_V(n) asm volatile("s_waitcnt vmcnt(" #n ")" ::: "memory")
; template <class Epi, class Sched, bool ALIGN_EPI = false, bool SP2 = false>
; __device__ __forceinline__ void gemm_phase(PG8_LAS unsigned char* lds, const Gemm g, const Sched& S, const Epi& E) {
;     ...
;             PG8_LDB(B0, 0, 0); PG8_LDB(B1, 0, 1); PG8_SCHED; PG8_LDA(At, 0, 0); PG8_STAGE(PG8_SA(1, 1), a1 + hstep, voffA);
;             PG8_WAIT_V(8); PG8_WAIT_L(0); PG8_BAR; PG8_MMA(0, 0, At, B0); PG8_MMA(0, 1, At, B1); PG8_BAR; PG8_SCHED;
;             PG8_LDA(At, 0, 1); PG8_STAGE(PG8_SB(0, 0), b2, voffB); PG8_STAGE(PG8_SB(0, 1), b2 + hstep, voffB); PG8_STAGE(PG8_SA(0, 0), a2, voffA);
;             PG8_WAIT_V(8); PG8_WAIT_L(0); PG8_BAR; PG8_MMA(1, 0, At, B0); PG8_MMA(1, 1, At, B1); PG8_BAR; PG8_SCHED;
;             PG8_LDB(B0, 1, 0); PG8_LDB(B1, 1, 1); PG8_SCHED; PG8_LDA(At, 1, 0); PG8_STAGE(PG8_SA(0, 1), a2 + hstep, voffA);
;             PG8_WAIT_V(8); PG8_WAIT_L(0); PG8_BAR; PG8_MMA(0, 0, At, B0); PG8_MMA(0, 1, At, B1); PG8_BAR; PG8_SCHED;
;             PG8_LDA(At, 1, 1); PG8_STAGE(PG8_SB(1, 0), b3, voffB); PG8_STAGE(PG8_SB(1, 1), b3 + hstep, voffB); PG8_STAGE(PG8_SA(1, 0), a3, voffA);
;             PG8_WAIT_V(8); PG8_WAIT_L(0); PG8_BAR; PG8_MMA(1, 0, At, B0); PG8_MMA(1, 1, At, B1); PG8_BAR; PG8_SCHED;
	s_setprio 1
	s_waitcnt lgkmcnt(0)
	v_mfma_f32_16x16x32_bf16 v[64:67], v[142:145], v[178:181], v[64:67]
	v_mfma_f32_16x16x32_bf16 v[60:63], v[154:157], v[178:181], v[60:63]
	v_mfma_f32_16x16x32_bf16 v[48:51], v[154:157], v[186:189], v[48:51]
	v_mfma_f32_16x16x32_bf16 v[56:59], v[142:145], v[186:189], v[56:59]
	v_mfma_f32_16x16x32_bf16 v[40:43], v[142:145], v[194:197], v[40:43]
	v_mfma_f32_16x16x32_bf16 v[32:35], v[154:157], v[194:197], v[32:35]
	v_mfma_f32_16x16x32_bf16 v[16:19], v[154:157], v[202:205], v[16:19]
	v_mfma_f32_16x16x32_bf16 v[24:27], v[142:145], v[202:205], v[24:27]
	v_mfma_f32_16x16x32_bf16 v[64:67], v[150:153], v[182:185], v[64:67]
	v_mfma_f32_16x16x32_bf16 v[60:63], v[158:161], v[182:185], v[60:63]
	v_mfma_f32_16x16x32_bf16 v[48:51], v[158:161], v[190:193], v[48:51]
	v_mfma_f32_16x16x32_bf16 v[56:59], v[150:153], v[190:193], v[56:59]
	v_mfma_f32_16x16x32_bf16 v[40:43], v[150:153], v[198:201], v[40:43]
	v_mfma_f32_16x16x32_bf16 v[32:35], v[158:161], v[198:201], v[32:35]
	v_mfma_f32_16x16x32_bf16 v[16:19], v[158:161], v[206:209], v[16:19]
	v_mfma_f32_16x16x32_bf16 v[24:27], v[150:153], v[206:209], v[24:27]
	s_setprio 0
	s_setprio 1
	v_mfma_f32_16x16x32_bf16 v[52:55], v[162:165], v[178:181], v[52:55]
	v_mfma_f32_16x16x32_bf16 v[44:47], v[170:173], v[178:181], v[44:47]
	v_mfma_f32_16x16x32_bf16 v[28:31], v[170:173], v[186:189], v[28:31]
	v_mfma_f32_16x16x32_bf16 v[36:39], v[162:165], v[186:189], v[36:39]
	v_mfma_f32_16x16x32_bf16 v[20:23], v[162:165], v[194:197], v[20:23]
	v_mfma_f32_16x16x32_bf16 v[12:15], v[170:173], v[194:197], v[12:15]
	v_mfma_f32_16x16x32_bf16 v[4:7], v[170:173], v[202:205], v[4:7]
	v_mfma_f32_16x16x32_bf16 v[8:11], v[162:165], v[202:205], v[8:11]
	v_mfma_f32_16x16x32_bf16 v[52:55], v[166:169], v[182:185], v[52:55]
	v_mfma_f32_16x16x32_bf16 v[44:47], v[174:177], v[182:185], v[44:47]
	v_mfma_f32_16x16x32_bf16 v[28:31], v[174:177], v[190:193], v[28:31]
	v_mfma_f32_16x16x32_bf16 v[36:39], v[166:169], v[190:193], v[36:39]
	v_mfma_f32_16x16x32_bf16 v[20:23], v[166:169], v[198:201], v[20:23]
	v_mfma_f32_16x16x32_bf16 v[12:15], v[174:177], v[198:201], v[12:15]
	v_mfma_f32_16x16x32_bf16 v[4:7], v[174:177], v[206:209], v[4:7]
	v_mfma_f32_16x16x32_bf16 v[8:11], v[166:169], v[206:209], v[8:11]
	s_setprio 0
	s_barrier
	s_add_i32 s57, 0, 0x18000
	v_add_u32_e32 v149, s57, v146
	s_add_i32 s58, 0, 0x1c000
	ds_read_b128 v[142:145], v149
	ds_read_b128 v[150:153], v149 offset:1024
	ds_read_b128 v[154:157], v149 offset:2048
	ds_read_b128 v[158:161], v149 offset:3072
	v_add_u32_e32 v149, s58, v146
	ds_read_b128 v[162:165], v149
	ds_read_b128 v[166:169], v149 offset:1024
	ds_read_b128 v[170:173], v149 offset:2048
	ds_read_b128 v[174:177], v149 offset:3072
	s_add_u32 s30, s46, 0x80000
	s_addc_u32 s31, s47, 0
	s_mov_b32 m0, s33
	v_lshl_add_u64 v[218:219], s[30:31], 0, v[136:137]
	ds_read_b128 v[178:181], v148 offset:32768
	ds_read_b128 v[182:185], v148 offset:33792
	ds_read_b128 v[186:189], v148 offset:34816
	ds_read_b128 v[190:193], v148 offset:35840
	ds_read_b128 v[194:197], v148 offset:36864
	ds_read_b128 v[198:201], v148 offset:37888
	ds_read_b128 v[202:205], v148 offset:38912
	ds_read_b128 v[206:209], v148 offset:39936
	global_load_lds_dwordx4 v[218:219], off
	v_lshl_add_u64 v[218:219], s[30:31], 0, v[134:135]
	s_mov_b32 m0, s37
	s_nop 0
	global_load_lds_dwordx4 v[218:219], off
	s_waitcnt vmcnt(8)
	s_waitcnt lgkmcnt(0)
	s_barrier
	s_setprio 1
	s_waitcnt lgkmcnt(0)
	v_mfma_f32_16x16x32_bf16 v[128:131], v[142:145], v[178:181], v[128:131]
	v_mfma_f32_16x16x32_bf16 v[124:127], v[154:157], v[178:181], v[124:127]
	v_mfma_f32_16x16x32_bf16 v[112:115], v[154:157], v[186:189], v[112:115]
	v_mfma_f32_16x16x32_bf16 v[120:123], v[142:145], v[186:189], v[120:123]
	v_mfma_f32_16x16x32_bf16 v[104:107], v[142:145], v[194:197], v[104:107]
	v_mfma_f32_16x16x32_bf16 v[96:99], v[154:157], v[194:197], v[96:99]
	v_mfma_f32_16x16x32_bf16 v[80:83], v[154:157], v[202:205], v[80:83]
	v_mfma_f32_16x16x32_bf16 v[88:91], v[142:145], v[202:205], v[88:91]
	v_mfma_f32_16x16x32_bf16 v[128:131], v[150:153], v[182:185], v[128:131]
	v_mfma_f32_16x16x32_bf16 v[124:127], v[158:161], v[182:185], v[124:127]
	v_mfma_f32_16x16x32_bf16 v[112:115], v[158:161], v[190:193], v[112:115]
	v_mfma_f32_16x16x32_bf16 v[120:123], v[150:153], v[190:193], v[120:123]
	v_mfma_f32_16x16x32_bf16 v[104:107], v[150:153], v[198:201], v[104:107]
	v_mfma_f32_16x16x32_bf16 v[96:99], v[158:161], v[198:201], v[96:99]
	v_mfma_f32_16x16x32_bf16 v[80:83], v[158:161], v[206:209], v[80:83]
	v_mfma_f32_16x16x32_bf16 v[88:91], v[150:153], v[206:209], v[88:91]
	s_setprio 0
	s_setprio 1
	v_mfma_f32_16x16x32_bf16 v[116:119], v[162:165], v[178:181], v[116:119]
	v_mfma_f32_16x16x32_bf16 v[108:111], v[170:173], v[178:181], v[108:111]
	v_mfma_f32_16x16x32_bf16 v[92:95], v[170:173], v[186:189], v[92:95]
	v_mfma_f32_16x16x32_bf16 v[100:103], v[162:165], v[186:189], v[100:103]
	v_mfma_f32_16x16x32_bf16 v[84:87], v[162:165], v[194:197], v[84:87]
	v_mfma_f32_16x16x32_bf16 v[76:79], v[170:173], v[194:197], v[76:79]
	v_mfma_f32_16x16x32_bf16 v[68:71], v[170:173], v[202:205], v[68:71]
	v_mfma_f32_16x16x32_bf16 v[72:75], v[162:165], v[202:205], v[72:75]
	v_mfma_f32_16x16x32_bf16 v[116:119], v[166:169], v[182:185], v[116:119]
	v_mfma_f32_16x16x32_bf16 v[108:111], v[174:177], v[182:185], v[108:111]
	v_mfma_f32_16x16x32_bf16 v[92:95], v[174:177], v[190:193], v[92:95]
	v_mfma_f32_16x16x32_bf16 v[100:103], v[166:169], v[190:193], v[100:103]
	v_mfma_f32_16x16x32_bf16 v[84:87], v[166:169], v[198:201], v[84:87]
	v_mfma_f32_16x16x32_bf16 v[76:79], v[174:177], v[198:201], v[76:79]
	v_mfma_f32_16x16x32_bf16 v[68:71], v[174:177], v[206:209], v[68:71]
	v_mfma_f32_16x16x32_bf16 v[72:75], v[166:169], v[206:209], v[72:75]
	s_setprio 0
	s_barrier
; #define PG8_STAGE(bufoff, gbase, voff) do { _Pragma("unroll") for (int _i = 0; _i < 2; ++_i) \
;         __builtin_amdgcn_global_load_lds((const unsigned*)((const char*)(gbase) + (voff)[_i]), (PG8_LAS unsigned*)(lds + (bufoff) + ldsw + _i * 8192), 16, 0, 0); } while (0)
; #define PG8_LDA(dst, b, h) do { _Pragma("unroll") for (int m = 0; m < 4; ++m) _Pragma("unroll") for (int k = 0; k < 2; ++k) dst[m][k] = *(const PG8_LAS bf16x8*)(lds + PG8_SA(b, h) + aoff + m * 2048 + k * 1024); } while (0)
; #define PG8_LDB(dst, b, h) do { _Pragma("unroll") for (int n = 0; n < 2; ++n) _Pragma("unroll") for (int k = 0; k < 2; ++k) dst[n][k] = *(const PG8_LAS bf16x8*)(lds + PG8_SB(b, h) + boff + n * 2048 + k * 1024); } while (0)
; #define PG8_MMA(ai, bj, At, Bt) do { __builtin_amdgcn_s_setprio(1); _Pragma("unroll") for (int m = 0; m < 4; ++m) _Pragma("unroll") for (int n = 0; n < 2; ++n) _Pragma("unroll") for (int k = 0; k < 2; ++k) \
;         acc[ai][bj][m][n] = __builtin_amdgcn_mfma_f32_16x16x32_bf16(Bt[n][k], At[m][k], acc[ai][bj][m][n], 0, 0, 0); __builtin_amdgcn_s_setprio(0); } while (0)
; #define PG8_WAIT_V(n) asm volatile("s_waitcnt vmcnt(" #n ")" ::: "memory")
; #define PG8_WAIT_L(n) asm volatile("s_waitcnt lgkmcnt(" #n ")" ::: "memory")
; #define PG8_BAR __builtin_amdgcn_s_barrier()
; #define PG8_SCHED __builtin_amdgcn_sched_barrier(0)
; template <class Epi, class Sched, bool ALIGN_EPI = false, bool SP2 = false>
; __device__ __forceinline__ void gemm_phase(PG8_LAS unsigned char* lds, const Gemm g, const Sched& S, const Epi& E) {
;     ...
;         for (int t = 0; t < nt; t += 2) {
;             const bool last = (t == nt - 2);
;             const char* a1 = cA + (size_t)(t + 1) * kstep;
;             const char* a2 = last ? nA : cA + (size_t)(t + 2) * kstep; const char* b2 = last ? nB : cB + (size_t)(t + 2) * kstep;
;     ...
;             PG8_LDB(B0, 1, 0); PG8_LDB(B1, 1, 1); PG8_SCHED; PG8_LDA(At, 1, 0); PG8_STAGE(PG8_SA(0, 1), a2 + hstep, voffA);
;             PG8_WAIT_V(8); PG8_WAIT_L(0); PG8_BAR; PG8_MMA(0, 0, At, B0); PG8_MMA(0, 1, At, B1); PG8_BAR; PG8_SCHED;
;             PG8_LDA(At, 1, 1); PG8_STAGE(PG8_SB(1, 0), b3, voffB); PG8_STAGE(PG8_SB(1, 1), b3 + hstep, voffB); PG8_STAGE(PG8_SA(1, 0), a3, voffA);
;             PG8_WAIT_V(8); PG8_WAIT_L(0); PG8_BAR; PG8_MMA(1, 0, At, B0); PG8_MMA(1, 1, At, B1); PG8_BAR; PG8_SCHED;
	s_add_i32 s30, s57, s10
	v_lshl_add_u64 v[210:211], v[210:211], 0, s[28:29]
	s_mov_b32 m0, s30
	ds_read_b128 v[178:181], v148 offset:49152
	ds_read_b128 v[182:185], v148 offset:50176
	ds_read_b128 v[186:189], v148 offset:51200
	ds_read_b128 v[190:193], v148 offset:52224
	ds_read_b128 v[194:197], v148 offset:53248
	ds_read_b128 v[198:201], v148 offset:54272
	ds_read_b128 v[202:205], v148 offset:55296
	ds_read_b128 v[206:209], v148 offset:56320
	global_load_lds_dwordx4 v[210:211], off
	s_add_i32 m0, s30, 0x2000
	s_add_u32 s20, s20, 0x80080
	v_lshl_add_u64 v[210:211], v[212:213], 0, s[28:29]
	s_addc_u32 s21, s21, 0
	s_add_i32 s30, s58, s10
	global_load_lds_dwordx4 v[210:211], off
	v_lshl_add_u64 v[210:211], s[20:21], 0, v[2:3]
	s_mov_b32 m0, s30
	s_nop 0
	global_load_lds_dwordx4 v[210:211], off
	v_lshl_add_u64 v[210:211], s[20:21], 0, v[132:133]
	s_add_i32 m0, s30, 0x2000
	s_nop 0
	global_load_lds_dwordx4 v[210:211], off
	v_lshl_add_u64 v[210:211], v[214:215], 0, s[28:29]
	s_mov_b32 m0, s18
	s_nop 0
	global_load_lds_dwordx4 v[210:211], off
	v_lshl_add_u64 v[210:211], v[216:217], 0, s[28:29]
	s_mov_b32 m0, s48
	s_nop 0
	global_load_lds_dwordx4 v[210:211], off
	s_waitcnt vmcnt(8)
	s_waitcnt lgkmcnt(0)
	s_barrier
	s_setprio 1
	s_waitcnt lgkmcnt(0)
	v_mfma_f32_16x16x32_bf16 v[64:67], v[142:145], v[178:181], v[64:67]
	v_mfma_f32_16x16x32_bf16 v[60:63], v[154:157], v[178:181], v[60:63]
	v_mfma_f32_16x16x32_bf16 v[48:51], v[154:157], v[186:189], v[48:51]
	v_mfma_f32_16x16x32_bf16 v[56:59], v[142:145], v[186:189], v[56:59]
	v_mfma_f32_16x16x32_bf16 v[40:43], v[142:145], v[194:197], v[40:43]
	v_mfma_f32_16x16x32_bf16 v[32:35], v[154:157], v[194:197], v[32:35]
	v_mfma_f32_16x16x32_bf16 v[16:19], v[154:157], v[202:205], v[16:19]
	v_mfma_f32_16x16x32_bf16 v[24:27], v[142:145], v[202:205], v[24:27]
	v_mfma_f32_16x16x32_bf16 v[64:67], v[150:153], v[182:185], v[64:67]
	v_mfma_f32_16x16x32_bf16 v[60:63], v[158:161], v[182:185], v[60:63]
	v_mfma_f32_16x16x32_bf16 v[48:51], v[158:161], v[190:193], v[48:51]
	v_mfma_f32_16x16x32_bf16 v[56:59], v[150:153], v[190:193], v[56:59]
	v_mfma_f32_16x16x32_bf16 v[40:43], v[150:153], v[198:201], v[40:43]
	v_mfma_f32_16x16x32_bf16 v[32:35], v[158:161], v[198:201], v[32:35]
	v_mfma_f32_16x16x32_bf16 v[16:19], v[158:161], v[206:209], v[16:19]
	v_mfma_f32_16x16x32_bf16 v[24:27], v[150:153], v[206:209], v[24:27]
	s_setprio 0
	s_setprio 1
	v_mfma_f32_16x16x32_bf16 v[52:55], v[162:165], v[178:181], v[52:55]
	v_mfma_f32_16x16x32_bf16 v[44:47], v[170:173], v[178:181], v[44:47]
	v_mfma_f32_16x16x32_bf16 v[28:31], v[170:173], v[186:189], v[28:31]
	v_mfma_f32_16x16x32_bf16 v[36:39], v[162:165], v[186:189], v[36:39]
	v_mfma_f32_16x16x32_bf16 v[20:23], v[162:165], v[194:197], v[20:23]
	v_mfma_f32_16x16x32_bf16 v[12:15], v[170:173], v[194:197], v[12:15]
	v_mfma_f32_16x16x32_bf16 v[4:7], v[170:173], v[202:205], v[4:7]
	v_mfma_f32_16x16x32_bf16 v[8:11], v[162:165], v[202:205], v[8:11]
	v_mfma_f32_16x16x32_bf16 v[52:55], v[166:169], v[182:185], v[52:55]
	v_mfma_f32_16x16x32_bf16 v[44:47], v[174:177], v[182:185], v[44:47]
	v_mfma_f32_16x16x32_bf16 v[28:31], v[174:177], v[190:193], v[28:31]
	v_mfma_f32_16x16x32_bf16 v[36:39], v[166:169], v[190:193], v[36:39]
	v_mfma_f32_16x16x32_bf16 v[20:23], v[166:169], v[198:201], v[20:23]
	v_mfma_f32_16x16x32_bf16 v[12:15], v[174:177], v[198:201], v[12:15]
	v_mfma_f32_16x16x32_bf16 v[4:7], v[174:177], v[206:209], v[4:7]
	v_mfma_f32_16x16x32_bf16 v[8:11], v[166:169], v[206:209], v[8:11]
	s_setprio 0
	s_barrier
	s_add_i32 s56, s56, 2
	s_add_u32 s54, s54, 0x100
	s_addc_u32 s55, s55, 0
	s_add_u32 s44, s44, 0x100
	s_addc_u32 s45, s45, 0
	s_cmp_gt_u32 s56, 29
	s_cbranch_scc0 .LBB0_310
	s_and_b64 vcc, exec, s[22:23]
	s_cbranch_vccz .LBB0_313
	s_barrier

; #define PG8_STAGE(bufoff, gbase, voff) do { _Pragma("unroll") for (int _i = 0; _i < 2; ++_i) \
;         __builtin_amdgcn_global_load_lds((const unsigned*)((const char*)(gbase) + (voff)[_i]), (PG8_LAS unsigned*)(lds + (bufoff) + ldsw + _i * 8192), 16, 0, 0); } while (0)
; #define PG8_LDA(dst, b, h) do { _Pragma("unroll") for (int m = 0; m < 4; ++m) _Pragma("unroll") for (int k = 0; k < 2; ++k) dst[m][k] = *(const PG8_LAS bf16x8*)(lds + PG8_SA(b, h) + aoff + m * 2048 + k * 1024); } while (0)
; #define PG8_LDB(dst, b, h) do { _Pragma("unroll") for (int n = 0; n < 2; ++n) _Pragma("unroll") for (int k = 0; k < 2; ++k) dst[n][k] = *(const PG8_LAS bf16x8*)(lds + PG8_SB(b, h) + boff + n * 2048 + k * 1024); } while (0)
; template <class Epi, class Sched, bool ALIGN_EPI = false, bool SP2 = false>
; __device__ __forceinline__ void gemm_phase(PG8_LAS unsigned char* lds, const Gemm g, const Sched& S, const Epi& E) {
;     ...
;         for (int t = 0; t < nt; t += 2) {
;             const bool last = (t == nt - 2);
;             const char* a1 = cA + (size_t)(t + 1) * kstep;
;             const char* a2 = last ? nA : cA + (size_t)(t + 2) * kstep; const char* b2 = last ? nB : cB + (size_t)(t + 2) * kstep;
;             const char* a3 = a2 + kstep; const char* b3 = b2 + kstep;
;             if (last && has_next) S.a_ready(nxt);
;             if constexpr (SP2) {
;             PG8_LDB(B0, 0, 0); PG8_LDB(B1, 0, 1); PG8_SCHED; PG8_LDA(At, 0, 0); PG8_STAGE(PG8_SA(1, 1), a1 + hstep, voffA);
;             PG8_WAIT_V(8); PG8_WAIT_L(0); PG8_BAR; PG8_MMA(0, 0, At, B0); PG8_MMA(0, 1, At, B1); PG8_BAR; PG8_SCHED;
;             PG8_LDA(At, 0, 1); PG8_STAGE(PG8_SB(0, 0), b2, voffB); PG8_STAGE(PG8_SB(0, 1), b2 + hstep, voffB); PG8_STAGE(PG8_SA(0, 0), a2, voffA);
;             PG8_WAIT_V(8); PG8_WAIT_L(0); PG8_BAR; PG8_MMA(1, 0, At, B0); PG8_MMA(1, 1, At, B1); PG8_BAR; PG8_SCHED;
;             PG8_LDB(B0, 1, 0); PG8_LDB(B1, 1, 1); PG8_SCHED; PG8_LDA(At, 1, 0); PG8_STAGE(PG8_SA(0, 1), a2 + hstep, voffA);
;             PG8_WAIT_V(8); PG8_WAIT_L(0); PG8_BAR; PG8_MMA(0, 0, At, B0); PG8_MMA(0, 1, At, B1); PG8_BAR; PG8_SCHED;
;             PG8_LDA(At, 1, 1); PG8_STAGE(PG8_SB(1, 0), b3, voffB); PG8_STAGE(PG8_SB(1, 1), b3 + hstep, voffB); PG8_STAGE(PG8_SA(1, 0), a3, voffA);
;             PG8_WAIT_V(8); PG8_WAIT_L(0); PG8_BAR; PG8_MMA(1, 0, At, B0); PG8_MMA(1, 1, At, B1); PG8_BAR; PG8_SCHED;
.LBB0_2046:
	s_add_u32 s20, s44, 0xfff80080
	s_addc_u32 s21, s45, -1
	s_add_i32 s30, 0, 0x10000
	s_cmp_eq_u32 s59, 28
	s_cselect_b32 s47, s12, s21
	s_cselect_b32 s46, s13, s20
	s_cselect_b32 s21, s23, s58
	s_cselect_b32 s20, s25, s33
	s_add_i32 s60, 0, 0x14000
	s_waitcnt vmcnt(0) lgkmcnt(0)
	v_add_u32_e32 v80, s30, v212
	v_add_u32_e32 v160, s60, v212
	ds_read_b128 v[60:63], v80
	ds_read_b128 v[64:67], v80 offset:1024
	ds_read_b128 v[76:79], v80 offset:2048
	ds_read_b128 v[80:83], v80 offset:3072
	ds_read_b128 v[148:151], v160
	ds_read_b128 v[152:155], v160 offset:1024
	ds_read_b128 v[156:159], v160 offset:2048
	ds_read_b128 v[160:163], v160 offset:3072
	v_lshl_add_u64 v[206:207], s[44:45], 0, v[188:189]
	s_add_i32 m0, s43, 0xc000
	ds_read_b128 v[164:167], v218
	ds_read_b128 v[168:171], v218 offset:1024
	ds_read_b128 v[172:175], v218 offset:2048
	ds_read_b128 v[176:179], v218 offset:3072
	ds_read_b128 v[190:193], v218 offset:4096
	ds_read_b128 v[194:197], v218 offset:5120
	ds_read_b128 v[198:201], v218 offset:6144
	ds_read_b128 v[202:205], v218 offset:7168
	global_load_lds_dwordx4 v[206:207], off
	v_lshl_add_u64 v[206:207], s[44:45], 0, v[186:187]
	s_add_i32 m0, s43, 0xe000
	s_nop 0
	global_load_lds_dwordx4 v[206:207], off
	s_waitcnt vmcnt(8)
	s_waitcnt lgkmcnt(0)
	s_barrier
	s_setprio 1
	s_waitcnt lgkmcnt(0)
	v_mfma_f32_16x16x32_bf16 v[144:147], v[60:63], v[164:167], v[144:147]
	v_mfma_f32_16x16x32_bf16 v[140:143], v[76:79], v[164:167], v[140:143]
	v_mfma_f32_16x16x32_bf16 v[132:135], v[76:79], v[172:175], v[132:135]
	v_mfma_f32_16x16x32_bf16 v[136:139], v[60:63], v[172:175], v[136:139]
	v_mfma_f32_16x16x32_bf16 v[112:115], v[60:63], v[190:193], v[112:115]
	v_mfma_f32_16x16x32_bf16 v[108:111], v[76:79], v[190:193], v[108:111]
	v_mfma_f32_16x16x32_bf16 v[100:103], v[76:79], v[198:201], v[100:103]
	v_mfma_f32_16x16x32_bf16 v[104:107], v[60:63], v[198:201], v[104:107]
	v_mfma_f32_16x16x32_bf16 v[144:147], v[64:67], v[168:171], v[144:147]
	v_mfma_f32_16x16x32_bf16 v[140:143], v[80:83], v[168:171], v[140:143]
	v_mfma_f32_16x16x32_bf16 v[132:135], v[80:83], v[176:179], v[132:135]
	v_mfma_f32_16x16x32_bf16 v[136:139], v[64:67], v[176:179], v[136:139]
	v_mfma_f32_16x16x32_bf16 v[112:115], v[64:67], v[194:197], v[112:115]
	v_mfma_f32_16x16x32_bf16 v[108:111], v[80:83], v[194:197], v[108:111]
	v_mfma_f32_16x16x32_bf16 v[100:103], v[80:83], v[202:205], v[100:103]
	v_mfma_f32_16x16x32_bf16 v[104:107], v[64:67], v[202:205], v[104:107]
	s_setprio 0
	s_setprio 1
	v_mfma_f32_16x16x32_bf16 v[128:131], v[148:151], v[164:167], v[128:131]
	v_mfma_f32_16x16x32_bf16 v[124:127], v[156:159], v[164:167], v[124:127]
	v_mfma_f32_16x16x32_bf16 v[116:119], v[156:159], v[172:175], v[116:119]
	v_mfma_f32_16x16x32_bf16 v[120:123], v[148:151], v[172:175], v[120:123]
	v_mfma_f32_16x16x32_bf16 v[96:99], v[148:151], v[190:193], v[96:99]
	v_mfma_f32_16x16x32_bf16 v[92:95], v[156:159], v[190:193], v[92:95]
	v_mfma_f32_16x16x32_bf16 v[84:87], v[156:159], v[198:201], v[84:87]
	v_mfma_f32_16x16x32_bf16 v[88:91], v[148:151], v[198:201], v[88:91]
	v_mfma_f32_16x16x32_bf16 v[128:131], v[152:155], v[168:171], v[128:131]
	v_mfma_f32_16x16x32_bf16 v[124:127], v[160:163], v[168:171], v[124:127]
	v_mfma_f32_16x16x32_bf16 v[116:119], v[160:163], v[176:179], v[116:119]
	v_mfma_f32_16x16x32_bf16 v[120:123], v[152:155], v[176:179], v[120:123]
	v_mfma_f32_16x16x32_bf16 v[96:99], v[152:155], v[194:197], v[96:99]
	v_mfma_f32_16x16x32_bf16 v[92:95], v[160:163], v[194:197], v[92:95]
	v_mfma_f32_16x16x32_bf16 v[84:87], v[160:163], v[202:205], v[84:87]
	v_mfma_f32_16x16x32_bf16 v[88:91], v[152:155], v[202:205], v[88:91]
	s_setprio 0
	s_barrier
	s_add_i32 s30, s30, s9
	v_lshl_add_u64 v[206:207], s[20:21], 0, v[2:3]
	s_mov_b32 m0, s30
	ds_read_b128 v[164:167], v218 offset:16384
	ds_read_b128 v[168:171], v218 offset:17408
	ds_read_b128 v[172:175], v218 offset:18432
	ds_read_b128 v[176:179], v218 offset:19456
	ds_read_b128 v[190:193], v218 offset:20480
	ds_read_b128 v[194:197], v218 offset:21504
	ds_read_b128 v[198:201], v218 offset:22528
	ds_read_b128 v[202:205], v218 offset:23552
	global_load_lds_dwordx4 v[206:207], off
	s_add_i32 m0, s30, 0x2000
	s_add_u32 s30, s20, 0x80000
	v_lshl_add_u64 v[208:209], s[20:21], 0, v[184:185]
	s_addc_u32 s31, s21, 0
	s_add_i32 s60, s60, s9
	global_load_lds_dwordx4 v[208:209], off
	v_lshl_add_u64 v[210:211], s[30:31], 0, v[2:3]
	s_mov_b32 m0, s60
	v_lshl_add_u64 v[214:215], s[46:47], 0, v[182:183]
	global_load_lds_dwordx4 v[210:211], off
	v_lshl_add_u64 v[210:211], s[30:31], 0, v[184:185]
	s_add_i32 m0, s60, 0x2000
	s_nop 0
	global_load_lds_dwordx4 v[210:211], off
	v_lshl_add_u64 v[210:211], s[46:47], 0, v[180:181]
	s_mov_b32 m0, s43
	s_nop 0
	global_load_lds_dwordx4 v[210:211], off
	s_mov_b32 m0, s50
	s_nop 0
	global_load_lds_dwordx4 v[214:215], off
	s_waitcnt vmcnt(8)
	s_waitcnt lgkmcnt(0)
	s_barrier
; #define PG8_STAGE(bufoff, gbase, voff) do { _Pragma("unroll") for (int _i = 0; _i < 2; ++_i) \
;         __builtin_amdgcn_global_load_lds((const unsigned*)((const char*)(gbase) + (voff)[_i]), (PG8_LAS unsigned*)(lds + (bufoff) + ldsw + _i * 8192), 16, 0, 0); } while (0)
; #define PG8_LDA(dst, b, h) do { _Pragma("unroll") for (int m = 0; m < 4; ++m) _Pragma("unroll") for (int k = 0; k < 2; ++k) dst[m][k] = *(const PG8_LAS bf16x8*)(lds + PG8_SA(b, h) + aoff + m * 2048 + k * 1024); } while (0)
; #define PG8_LDB(dst, b, h) do { _Pragma("unroll") for (int n = 0; n < 2; ++n) _Pragma("unroll") for (int k = 0; k < 2; ++k) dst[n][k] = *(const PG8_LAS bf16x8*)(lds + PG8_SB(b, h) + boff + n * 2048 + k * 1024); } while (0)
; #define PG8_MMA(ai, bj, At, Bt) do { __builtin_amdgcn_s_setprio(1); _Pragma("unroll") for (int m = 0; m < 4; ++m) _Pragma("unroll") for (int n = 0; n < 2; ++n) _Pragma("unroll") for (int k = 0; k < 2; ++k) \
;         acc[ai][bj][m][n] = __builtin_amdgcn_mfma_f32_16x16x32_bf16(Bt[n][k], At[m][k], acc[ai][bj][m][n], 0, 0, 0); __builtin_amdgcn_s_setprio(0); } while (0)
; #define PG8_WAIT_V(n) asm volatile("s_waitcnt vmcnt(" #n ")" ::: "memory")
; #define PG8_WAIT_L(n) asm volatile("s_waitcnt lgkmcnt(" #n ")" ::: "memory")
; #define PG8_BAR __builtin_amdgcn_s_barrier()
; #define PG8_SCHED __builtin_amdgcn_sched_barrier(0)
; template <class Epi, class Sched, bool ALIGN_EPI = false, bool SP2 = false>
; __device__ __forceinline__ void gemm_phase(PG8_LAS unsigned char* lds, const Gemm g, const Sched& S, const Epi& E) {
;     ...
;             PG8_LDA(At, 0, 1); PG8_STAGE(PG8_SB(0, 0), b2, voffB); PG8_STAGE(PG8_SB(0, 1), b2 + hstep, voffB); PG8_STAGE(PG8_SA(0, 0), a2, voffA);
;             PG8_WAIT_V(8); PG8_WAIT_L(0); PG8_BAR; PG8_MMA(1, 0, At, B0); PG8_MMA(1, 1, At, B1); PG8_BAR; PG8_SCHED;
;             PG8_LDB(B0, 1, 0); PG8_LDB(B1, 1, 1); PG8_SCHED; PG8_LDA(At, 1, 0); PG8_STAGE(PG8_SA(0, 1), a2 + hstep, voffA);
;             PG8_WAIT_V(8); PG8_WAIT_L(0); PG8_BAR; PG8_MMA(0, 0, At, B0); PG8_MMA(0, 1, At, B1); PG8_BAR; PG8_SCHED;
;             PG8_LDA(At, 1, 1); PG8_STAGE(PG8_SB(1, 0), b3, voffB); PG8_STAGE(PG8_SB(1, 1), b3 + hstep, voffB); PG8_STAGE(PG8_SA(1, 0), a3, voffA);
;             PG8_WAIT_V(8); PG8_WAIT_L(0); PG8_BAR; PG8_MMA(1, 0, At, B0); PG8_MMA(1, 1, At, B1); PG8_BAR; PG8_SCHED;
	s_setprio 1
	s_waitcnt lgkmcnt(0)
	v_mfma_f32_16x16x32_bf16 v[72:75], v[60:63], v[164:167], v[72:75]
	v_mfma_f32_16x16x32_bf16 v[68:71], v[76:79], v[164:167], v[68:71]
	v_mfma_f32_16x16x32_bf16 v[52:55], v[76:79], v[172:175], v[52:55]
	v_mfma_f32_16x16x32_bf16 v[56:59], v[60:63], v[172:175], v[56:59]
	v_mfma_f32_16x16x32_bf16 v[32:35], v[60:63], v[190:193], v[32:35]
	v_mfma_f32_16x16x32_bf16 v[28:31], v[76:79], v[190:193], v[28:31]
	v_mfma_f32_16x16x32_bf16 v[20:23], v[76:79], v[198:201], v[20:23]
	v_mfma_f32_16x16x32_bf16 v[24:27], v[60:63], v[198:201], v[24:27]
	v_mfma_f32_16x16x32_bf16 v[72:75], v[64:67], v[168:171], v[72:75]
	v_mfma_f32_16x16x32_bf16 v[68:71], v[80:83], v[168:171], v[68:71]
	v_mfma_f32_16x16x32_bf16 v[52:55], v[80:83], v[176:179], v[52:55]
	v_mfma_f32_16x16x32_bf16 v[56:59], v[64:67], v[176:179], v[56:59]
	v_mfma_f32_16x16x32_bf16 v[32:35], v[64:67], v[194:197], v[32:35]
	v_mfma_f32_16x16x32_bf16 v[28:31], v[80:83], v[194:197], v[28:31]
	v_mfma_f32_16x16x32_bf16 v[20:23], v[80:83], v[202:205], v[20:23]
	v_mfma_f32_16x16x32_bf16 v[24:27], v[64:67], v[202:205], v[24:27]
	s_setprio 0
	s_setprio 1
	v_mfma_f32_16x16x32_bf16 v[48:51], v[148:151], v[164:167], v[48:51]
	v_mfma_f32_16x16x32_bf16 v[44:47], v[156:159], v[164:167], v[44:47]
	v_mfma_f32_16x16x32_bf16 v[36:39], v[156:159], v[172:175], v[36:39]
	v_mfma_f32_16x16x32_bf16 v[40:43], v[148:151], v[172:175], v[40:43]
	v_mfma_f32_16x16x32_bf16 v[16:19], v[148:151], v[190:193], v[16:19]
	v_mfma_f32_16x16x32_bf16 v[12:15], v[156:159], v[190:193], v[12:15]
	v_mfma_f32_16x16x32_bf16 v[4:7], v[156:159], v[198:201], v[4:7]
	v_mfma_f32_16x16x32_bf16 v[8:11], v[148:151], v[198:201], v[8:11]
	v_mfma_f32_16x16x32_bf16 v[48:51], v[152:155], v[168:171], v[48:51]
	v_mfma_f32_16x16x32_bf16 v[44:47], v[160:163], v[168:171], v[44:47]
	v_mfma_f32_16x16x32_bf16 v[36:39], v[160:163], v[176:179], v[36:39]
	v_mfma_f32_16x16x32_bf16 v[40:43], v[152:155], v[176:179], v[40:43]
	v_mfma_f32_16x16x32_bf16 v[16:19], v[152:155], v[194:197], v[16:19]
	v_mfma_f32_16x16x32_bf16 v[12:15], v[160:163], v[194:197], v[12:15]
	v_mfma_f32_16x16x32_bf16 v[4:7], v[160:163], v[202:205], v[4:7]
	v_mfma_f32_16x16x32_bf16 v[8:11], v[152:155], v[202:205], v[8:11]
	s_setprio 0
	s_barrier
	s_add_i32 s60, 0, 0x18000
	s_add_i32 s61, 0, 0x1c000
	v_add_u32_e32 v80, s60, v212
	v_add_u32_e32 v160, s61, v212
	ds_read_b128 v[60:63], v80
	ds_read_b128 v[64:67], v80 offset:1024
	ds_read_b128 v[76:79], v80 offset:2048
	ds_read_b128 v[80:83], v80 offset:3072
	ds_read_b128 v[148:151], v160
	ds_read_b128 v[152:155], v160 offset:1024
	ds_read_b128 v[156:159], v160 offset:2048
	ds_read_b128 v[160:163], v160 offset:3072
	s_add_u32 s30, s46, 0x80000
	s_addc_u32 s31, s47, 0
	s_mov_b32 m0, s51
	v_lshl_add_u64 v[216:217], s[30:31], 0, v[180:181]
	ds_read_b128 v[164:167], v218 offset:32768
	ds_read_b128 v[168:171], v218 offset:33792
	ds_read_b128 v[172:175], v218 offset:34816
	ds_read_b128 v[176:179], v218 offset:35840
	ds_read_b128 v[190:193], v218 offset:36864
	ds_read_b128 v[194:197], v218 offset:37888
	ds_read_b128 v[198:201], v218 offset:38912
	ds_read_b128 v[202:205], v218 offset:39936
	global_load_lds_dwordx4 v[216:217], off
	v_lshl_add_u64 v[216:217], s[30:31], 0, v[182:183]
	s_mov_b32 m0, s52
	s_nop 0
	global_load_lds_dwordx4 v[216:217], off
	s_waitcnt vmcnt(8)
	s_waitcnt lgkmcnt(0)
	s_barrier
	s_setprio 1
	s_waitcnt lgkmcnt(0)
	v_mfma_f32_16x16x32_bf16 v[144:147], v[60:63], v[164:167], v[144:147]
	v_mfma_f32_16x16x32_bf16 v[140:143], v[76:79], v[164:167], v[140:143]
	v_mfma_f32_16x16x32_bf16 v[132:135], v[76:79], v[172:175], v[132:135]
	v_mfma_f32_16x16x32_bf16 v[136:139], v[60:63], v[172:175], v[136:139]
	v_mfma_f32_16x16x32_bf16 v[112:115], v[60:63], v[190:193], v[112:115]
	v_mfma_f32_16x16x32_bf16 v[108:111], v[76:79], v[190:193], v[108:111]
	v_mfma_f32_16x16x32_bf16 v[100:103], v[76:79], v[198:201], v[100:103]
	v_mfma_f32_16x16x32_bf16 v[104:107], v[60:63], v[198:201], v[104:107]
	v_mfma_f32_16x16x32_bf16 v[144:147], v[64:67], v[168:171], v[144:147]
	v_mfma_f32_16x16x32_bf16 v[140:143], v[80:83], v[168:171], v[140:143]
	v_mfma_f32_16x16x32_bf16 v[132:135], v[80:83], v[176:179], v[132:135]
	v_mfma_f32_16x16x32_bf16 v[136:139], v[64:67], v[176:179], v[136:139]
	v_mfma_f32_16x16x32_bf16 v[112:115], v[64:67], v[194:197], v[112:115]
	v_mfma_f32_16x16x32_bf16 v[108:111], v[80:83], v[194:197], v[108:111]
	v_mfma_f32_16x16x32_bf16 v[100:103], v[80:83], v[202:205], v[100:103]
	v_mfma_f32_16x16x32_bf16 v[104:107], v[64:67], v[202:205], v[104:107]
	s_setprio 0
	s_setprio 1
	v_mfma_f32_16x16x32_bf16 v[128:131], v[148:151], v[164:167], v[128:131]
	v_mfma_f32_16x16x32_bf16 v[124:127], v[156:159], v[164:167], v[124:127]
	v_mfma_f32_16x16x32_bf16 v[116:119], v[156:159], v[172:175], v[116:119]
	v_mfma_f32_16x16x32_bf16 v[120:123], v[148:151], v[172:175], v[120:123]
	v_mfma_f32_16x16x32_bf16 v[96:99], v[148:151], v[190:193], v[96:99]
	v_mfma_f32_16x16x32_bf16 v[92:95], v[156:159], v[190:193], v[92:95]
	v_mfma_f32_16x16x32_bf16 v[84:87], v[156:159], v[198:201], v[84:87]
	v_mfma_f32_16x16x32_bf16 v[88:91], v[148:151], v[198:201], v[88:91]
	v_mfma_f32_16x16x32_bf16 v[128:131], v[152:155], v[168:171], v[128:131]
	v_mfma_f32_16x16x32_bf16 v[124:127], v[160:163], v[168:171], v[124:127]
	v_mfma_f32_16x16x32_bf16 v[116:119], v[160:163], v[176:179], v[116:119]
	v_mfma_f32_16x16x32_bf16 v[120:123], v[152:155], v[176:179], v[120:123]
	v_mfma_f32_16x16x32_bf16 v[96:99], v[152:155], v[194:197], v[96:99]
	v_mfma_f32_16x16x32_bf16 v[92:95], v[160:163], v[194:197], v[92:95]
	v_mfma_f32_16x16x32_bf16 v[84:87], v[160:163], v[202:205], v[84:87]
	v_mfma_f32_16x16x32_bf16 v[88:91], v[152:155], v[202:205], v[88:91]
	s_setprio 0
	s_barrier
; #define PG8_STAGE(bufoff, gbase, voff) do { _Pragma("unroll") for (int _i = 0; _i < 2; ++_i) \
;         __builtin_amdgcn_global_load_lds((const unsigned*)((const char*)(gbase) + (voff)[_i]), (PG8_LAS unsigned*)(lds + (bufoff) + ldsw + _i * 8192), 16, 0, 0); } while (0)
; #define PG8_LDA(dst, b, h) do { _Pragma("unroll") for (int m = 0; m < 4; ++m) _Pragma("unroll") for (int k = 0; k < 2; ++k) dst[m][k] = *(const PG8_LAS bf16x8*)(lds + PG8_SA(b, h) + aoff + m * 2048 + k * 1024); } while (0)
; #define PG8_LDB(dst, b, h) do { _Pragma("unroll") for (int n = 0; n < 2; ++n) _Pragma("unroll") for (int k = 0; k < 2; ++k) dst[n][k] = *(const PG8_LAS bf16x8*)(lds + PG8_SB(b, h) + boff + n * 2048 + k * 1024); } while (0)
; #define PG8_MMA(ai, bj, At, Bt) do { __builtin_amdgcn_s_setprio(1); _Pragma("unroll") for (int m = 0; m < 4; ++m) _Pragma("unroll") for (int n = 0; n < 2; ++n) _Pragma("unroll") for (int k = 0; k < 2; ++k) \
;         acc[ai][bj][m][n] = __builtin_amdgcn_mfma_f32_16x16x32_bf16(Bt[n][k], At[m][k], acc[ai][bj][m][n], 0, 0, 0); __builtin_amdgcn_s_setprio(0); } while (0)
; #define PG8_WAIT_V(n) asm volatile("s_waitcnt vmcnt(" #n ")" ::: "memory")
;     __device__ __forceinline__ void operator()(const f32x4 (&acc)[2][2][4][2], const Unit& u, int wr, int wc, int fr, int fq) const {
;         const int row0 = u.pm * BM + wr * 64 + fr; const int col0 = u.pn * BM + wc * 32 + 8 * fq;
;         const float* gp = gate + (size_t)((u.pm * BM) >> 12) * gstride + col0;
;         f32x4 gv[2][2];
; #pragma unroll
;         for (int bj = 0; bj < 2; ++bj)
; #pragma unroll
;             for (int n = 0; n < 2; ++n) gv[bj][n] = *(const f32x4*)(gp + bj * HALF + n * 4);
; template <class Epi, class Sched, bool ALIGN_EPI = false, bool SP2 = false>
; __device__ __forceinline__ void gemm_phase(PG8_LAS unsigned char* lds, const Gemm g, const Sched& S, const Epi& E) {
;     ...
;             PG8_LDB(B0, 1, 0); PG8_LDB(B1, 1, 1); PG8_SCHED; PG8_LDA(At, 1, 0); PG8_STAGE(PG8_SA(0, 1), a2 + hstep, voffA);
;             PG8_WAIT_V(8); PG8_WAIT_L(0); PG8_BAR; PG8_MMA(0, 0, At, B0); PG8_MMA(0, 1, At, B1); PG8_BAR; PG8_SCHED;
;             PG8_LDA(At, 1, 1); PG8_STAGE(PG8_SB(1, 0), b3, voffB); PG8_STAGE(PG8_SB(1, 1), b3 + hstep, voffB); PG8_STAGE(PG8_SA(1, 0), a3, voffA);
;             PG8_WAIT_V(8); PG8_WAIT_L(0); PG8_BAR; PG8_MMA(1, 0, At, B0); PG8_MMA(1, 1, At, B1); PG8_BAR; PG8_SCHED;
	s_add_i32 s30, s60, s9
	v_lshl_add_u64 v[206:207], v[206:207], 0, s[28:29]
	s_mov_b32 m0, s30
	ds_read_b128 v[164:167], v218 offset:49152
	ds_read_b128 v[168:171], v218 offset:50176
	ds_read_b128 v[172:175], v218 offset:51200
	ds_read_b128 v[176:179], v218 offset:52224
	ds_read_b128 v[190:193], v218 offset:53248
	ds_read_b128 v[194:197], v218 offset:54272
	ds_read_b128 v[198:201], v218 offset:55296
	ds_read_b128 v[202:205], v218 offset:56320
	global_load_lds_dwordx4 v[206:207], off
	s_add_i32 m0, s30, 0x2000
	s_add_u32 s20, s20, 0x80080
	v_lshl_add_u64 v[206:207], v[208:209], 0, s[28:29]
	s_addc_u32 s21, s21, 0
	s_add_i32 s30, s61, s9
	global_load_lds_dwordx4 v[206:207], off
	v_lshl_add_u64 v[206:207], s[20:21], 0, v[2:3]
	s_mov_b32 m0, s30
	s_nop 0
	global_load_lds_dwordx4 v[206:207], off
	v_lshl_add_u64 v[206:207], s[20:21], 0, v[184:185]
	s_add_i32 m0, s30, 0x2000
	s_nop 0
	global_load_lds_dwordx4 v[206:207], off
	v_lshl_add_u64 v[206:207], v[210:211], 0, s[28:29]
	s_mov_b32 m0, s54
	s_nop 0
	global_load_lds_dwordx4 v[206:207], off
	v_lshl_add_u64 v[206:207], v[214:215], 0, s[28:29]
	s_mov_b32 m0, s55
	s_nop 0
	global_load_lds_dwordx4 v[206:207], off
	s_waitcnt vmcnt(8)
	s_waitcnt lgkmcnt(0)
	s_barrier
	s_setprio 1
	s_waitcnt lgkmcnt(0)
	v_mfma_f32_16x16x32_bf16 v[72:75], v[60:63], v[164:167], v[72:75]
	v_mfma_f32_16x16x32_bf16 v[68:71], v[76:79], v[164:167], v[68:71]
	v_mfma_f32_16x16x32_bf16 v[52:55], v[76:79], v[172:175], v[52:55]
	v_mfma_f32_16x16x32_bf16 v[56:59], v[60:63], v[172:175], v[56:59]
	v_mfma_f32_16x16x32_bf16 v[32:35], v[60:63], v[190:193], v[32:35]
	v_mfma_f32_16x16x32_bf16 v[28:31], v[76:79], v[190:193], v[28:31]
	v_mfma_f32_16x16x32_bf16 v[20:23], v[76:79], v[198:201], v[20:23]
	v_mfma_f32_16x16x32_bf16 v[24:27], v[60:63], v[198:201], v[24:27]
	v_mfma_f32_16x16x32_bf16 v[72:75], v[64:67], v[168:171], v[72:75]
	v_mfma_f32_16x16x32_bf16 v[68:71], v[80:83], v[168:171], v[68:71]
	v_mfma_f32_16x16x32_bf16 v[52:55], v[80:83], v[176:179], v[52:55]
	v_mfma_f32_16x16x32_bf16 v[56:59], v[64:67], v[176:179], v[56:59]
	v_mfma_f32_16x16x32_bf16 v[32:35], v[64:67], v[194:197], v[32:35]
	v_mfma_f32_16x16x32_bf16 v[28:31], v[80:83], v[194:197], v[28:31]
	v_mfma_f32_16x16x32_bf16 v[20:23], v[80:83], v[202:205], v[20:23]
	v_mfma_f32_16x16x32_bf16 v[24:27], v[64:67], v[202:205], v[24:27]
	s_setprio 0
	s_setprio 1
	v_mfma_f32_16x16x32_bf16 v[48:51], v[148:151], v[164:167], v[48:51]
	v_mfma_f32_16x16x32_bf16 v[44:47], v[156:159], v[164:167], v[44:47]
	v_mfma_f32_16x16x32_bf16 v[36:39], v[156:159], v[172:175], v[36:39]
	v_mfma_f32_16x16x32_bf16 v[40:43], v[148:151], v[172:175], v[40:43]
	v_mfma_f32_16x16x32_bf16 v[16:19], v[148:151], v[190:193], v[16:19]
	v_mfma_f32_16x16x32_bf16 v[12:15], v[156:159], v[190:193], v[12:15]
	v_mfma_f32_16x16x32_bf16 v[4:7], v[156:159], v[198:201], v[4:7]
	v_mfma_f32_16x16x32_bf16 v[8:11], v[148:151], v[198:201], v[8:11]
	v_mfma_f32_16x16x32_bf16 v[48:51], v[152:155], v[168:171], v[48:51]
	v_mfma_f32_16x16x32_bf16 v[44:47], v[160:163], v[168:171], v[44:47]
	v_mfma_f32_16x16x32_bf16 v[36:39], v[160:163], v[176:179], v[36:39]
	v_mfma_f32_16x16x32_bf16 v[40:43], v[152:155], v[176:179], v[40:43]
	v_mfma_f32_16x16x32_bf16 v[16:19], v[152:155], v[194:197], v[16:19]
	v_mfma_f32_16x16x32_bf16 v[12:15], v[160:163], v[194:197], v[12:15]
	v_mfma_f32_16x16x32_bf16 v[4:7], v[160:163], v[202:205], v[4:7]
	v_mfma_f32_16x16x32_bf16 v[8:11], v[152:155], v[202:205], v[8:11]
	s_setprio 0
	s_barrier
	s_add_i32 s59, s59, 2
	s_add_u32 s33, s33, 0x100
	s_addc_u32 s58, s58, 0
	s_add_u32 s44, s44, 0x100
	s_addc_u32 s45, s45, 0
	s_cmp_gt_u32 s59, 29
	s_cbranch_scc0 .LBB0_2046
	v_lshl_or_b32 v202, s4, 8, v213
	s_ashr_i32 s4, s42, 4
	s_mul_hi_i32 s13, s4, 0xc000
	s_mul_i32 s4, s4, 0xc000
	s_add_u32 s12, s18, s4
	s_addc_u32 s13, s53, s13
	v_ashrrev_i32_e32 v203, 31, v202
	v_lshl_add_u64 v[60:61], v[202:203], 2, s[12:13]
	flat_load_dwordx4 v[80:83], v[60:61]
	flat_load_dwordx4 v[76:79], v[60:61] offset:16
	flat_load_dwordx4 v[64:67], v[60:61] offset:512
	s_nop 0
	flat_load_dwordx4 v[60:63], v[60:61] offset:528
	v_lshl_add_u32 v192, s42, 8, v1
	v_ashrrev_i32_e32 v193, 31, v192
	v_or_b32_e32 v198, 16, v192
	v_or_b32_e32 v196, 32, v192
	v_or_b32_e32 v194, 48, v192
	v_lshlrev_b64 v[200:201], 11, v[192:193]
	s_and_b64 vcc, exec, s[16:17]
	v_lshlrev_b64 v[190:191], 1, v[202:203]
	v_ashrrev_i32_e32 v199, 31, v198
	v_ashrrev_i32_e32 v197, 31, v196
	v_ashrrev_i32_e32 v195, 31, v194
	s_cbranch_vccz .LBB0_2049
; __device__ __forceinline__ unsigned cvt_pk_bf16(float lo, float hi) { unsigned r; asm volatile("v_cvt_pk_bf16_f32 %0, %1, %2" : "=v"(r) : "v"(lo), "v"(hi)); return r; }
;     __device__ __forceinline__ void operator()(const f32x4 (&acc)[2][2][4][2], const Unit& u, int wr, int wc, int fr, int fq) const {
;     ...
;         } else { const bf16_t* bp = (const bf16_t*)base;
; #pragma unroll
;             for (int ai = 0; ai < 2; ++ai) { u32x4 bs[4][2];
; #pragma unroll
;                 for (int m = 0; m < 4; ++m) { const size_t off = (size_t)(row0 + ai * HALF + m * 16) * ldc + col0;
; #pragma unroll
;                     for (int bj = 0; bj < 2; ++bj) bs[m][bj] = *(const u32x4*)(bp + off + bj * HALF); }
; #pragma unroll
;                 for (int m = 0; m < 4; ++m) { const size_t off = (size_t)(row0 + ai * HALF + m * 16) * ldc + col0;
; #pragma unroll
;                     for (int bj = 0; bj < 2; ++bj) { const u32x4 r = bs[m][bj]; const f32x4 a0 = acc[ai][bj][m][0], a1 = acc[ai][bj][m][1];
;                         u32x4 w;
;                         w.x = cvt_pk_bf16(__builtin_bit_cast(float, r.x << 16) + gv[bj][0][0] * a0[0], __builtin_bit_cast(float, r.x & 0xffff0000u) + gv[bj][0][1] * a0[1]);
;                         w.y = cvt_pk_bf16(__builtin_bit_cast(float, r.y << 16) + gv[bj][0][2] * a0[2], __builtin_bit_cast(float, r.y & 0xffff0000u) + gv[bj][0][3] * a0[3]);
;                         w.z = cvt_pk_bf16(__builtin_bit_cast(float, r.z << 16) + gv[bj][1][0] * a1[0], __builtin_bit_cast(float, r.z & 0xffff0000u) + gv[bj][1][1] * a1[1]);
;                         w.w = cvt_pk_bf16(__builtin_bit_cast(float, r.w << 16) + gv[bj][1][2] * a1[2], __builtin_bit_cast(float, r.w & 0xffff0000u) + gv[bj][1][3] * a1[3]);
;                         *(u32x4*)(out + off + bj * HALF) = w; } }
;                 asm volatile("" ::: "memory"); }
	v_lshl_add_u64 v[204:205], s[26:27], 0, v[190:191]
	v_lshlrev_b64 v[156:157], 1, v[200:201]
	v_lshl_add_u64 v[148:149], v[204:205], 0, v[156:157]
	v_lshlrev_b64 v[152:153], 12, v[198:199]
	flat_load_dwordx4 v[172:175], v[148:149]
	flat_load_dwordx4 v[168:171], v[148:149] offset:256
	v_lshl_add_u64 v[148:149], v[204:205], 0, v[152:153]
	flat_load_dwordx4 v[164:167], v[148:149]
	s_nop 0
	flat_load_dwordx4 v[148:151], v[148:149] offset:256
	v_lshlrev_b64 v[208:209], 12, v[196:197]
	v_lshlrev_b64 v[206:207], 12, v[194:195]
	v_lshl_add_u64 v[154:155], v[204:205], 0, v[208:209]
	v_lshl_add_u64 v[210:211], v[204:205], 0, v[206:207]
	v_lshl_add_u64 v[214:215], s[14:15], 0, v[156:157]
	v_lshl_add_u64 v[216:217], s[14:15], 0, v[152:153]
	flat_load_dwordx4 v[176:179], v[154:155]
	flat_load_dwordx4 v[160:163], v[154:155] offset:256
	flat_load_dwordx4 v[156:159], v[210:211]
	s_nop 0
	flat_load_dwordx4 v[152:155], v[210:211] offset:256
	v_lshl_add_u64 v[210:211], v[216:217], 0, v[190:191]
	v_lshl_add_u64 v[214:215], v[214:215], 0, v[190:191]
	s_mov_b64 s[12:13], 0x80000
	s_waitcnt vmcnt(0) lgkmcnt(0)
	v_lshlrev_b32_e32 v216, 16, v172
	v_and_b32_e32 v172, 0xffff0000, v172
	v_lshlrev_b32_e32 v217, 16, v173
	v_and_b32_e32 v173, 0xffff0000, v173
	v_lshlrev_b32_e32 v219, 16, v174
	v_and_b32_e32 v174, 0xffff0000, v174
	v_lshlrev_b32_e32 v220, 16, v175
	v_and_b32_e32 v175, 0xffff0000, v175
	v_lshlrev_b32_e32 v221, 16, v168
	v_and_b32_e32 v168, 0xffff0000, v168
	v_lshlrev_b32_e32 v225, 16, v164
	v_and_b32_e32 v226, 0xffff0000, v164
	v_fmac_f32_e32 v216, v144, v80
	v_fmac_f32_e32 v172, v145, v81
	v_cvt_pk_bf16_f32 v164, v216, v172
	v_lshlrev_b32_e32 v222, 16, v169
	v_and_b32_e32 v169, 0xffff0000, v169
	v_lshlrev_b32_e32 v223, 16, v170
	v_and_b32_e32 v170, 0xffff0000, v170
	v_lshlrev_b32_e32 v224, 16, v171
	v_and_b32_e32 v171, 0xffff0000, v171
	v_lshlrev_b32_e32 v227, 16, v165
	v_and_b32_e32 v229, 0xffff0000, v165
	v_lshlrev_b32_e32 v232, 16, v166
	v_and_b32_e32 v233, 0xffff0000, v166
	v_lshlrev_b32_e32 v240, 16, v167
	v_and_b32_e32 v241, 0xffff0000, v167
	v_fmac_f32_e32 v217, v146, v82
	v_fmac_f32_e32 v173, v147, v83
	v_fmac_f32_e32 v219, v140, v76
	v_fmac_f32_e32 v174, v141, v77
	v_fmac_f32_e32 v220, v142, v78
	v_fmac_f32_e32 v175, v143, v79
	v_fmac_f32_e32 v221, v128, v64
	v_fmac_f32_e32 v168, v129, v65
	v_cvt_pk_bf16_f32 v165, v217, v173
	v_cvt_pk_bf16_f32 v166, v219, v174
	v_cvt_pk_bf16_f32 v167, v220, v175
	flat_store_dwordx4 v[214:215], v[164:167]
	v_fmac_f32_e32 v222, v130, v66
	v_fmac_f32_e32 v169, v131, v67
	v_cvt_pk_bf16_f32 v164, v221, v168
	v_fmac_f32_e32 v223, v124, v60
	v_fmac_f32_e32 v170, v125, v61
	v_fmac_f32_e32 v224, v126, v62
	v_fmac_f32_e32 v171, v127, v63
	v_fmac_f32_e32 v225, v136, v80
	v_fmac_f32_e32 v226, v137, v81
	v_cvt_pk_bf16_f32 v165, v222, v169
	v_cvt_pk_bf16_f32 v166, v223, v170
	v_cvt_pk_bf16_f32 v167, v224, v171
	flat_store_dwordx4 v[214:215], v[164:167] offset:256
	v_lshlrev_b32_e32 v242, 16, v148
	v_and_b32_e32 v148, 0xffff0000, v148
	v_cvt_pk_bf16_f32 v164, v225, v226
	v_fmac_f32_e32 v227, v138, v82
	v_fmac_f32_e32 v229, v139, v83
	v_fmac_f32_e32 v232, v132, v76
	v_fmac_f32_e32 v233, v133, v77
	v_fmac_f32_e32 v240, v134, v78
	v_fmac_f32_e32 v241, v135, v79
	v_cvt_pk_bf16_f32 v165, v227, v229
	v_cvt_pk_bf16_f32 v166, v232, v233
	v_cvt_pk_bf16_f32 v167, v240, v241
	flat_store_dwordx4 v[210:211], v[164:167]
	v_fmac_f32_e32 v148, v121, v65
	v_fmac_f32_e32 v242, v120, v64
	v_lshlrev_b32_e32 v164, 16, v149
	v_and_b32_e32 v149, 0xffff0000, v149
	v_fmac_f32_e32 v164, v122, v66
	v_fmac_f32_e32 v149, v123, v67
	v_cvt_pk_bf16_f32 v148, v242, v148
	v_cvt_pk_bf16_f32 v149, v164, v149
	v_lshlrev_b32_e32 v164, 16, v150
	v_and_b32_e32 v150, 0xffff0000, v150
	v_fmac_f32_e32 v164, v116, v60
	v_fmac_f32_e32 v150, v117, v61
	v_cvt_pk_bf16_f32 v150, v164, v150
	v_lshlrev_b32_e32 v164, 16, v151
	v_and_b32_e32 v151, 0xffff0000, v151
	v_fmac_f32_e32 v151, v119, v63
	v_fmac_f32_e32 v164, v118, v62
	v_cvt_pk_bf16_f32 v151, v164, v151
	flat_store_dwordx4 v[210:211], v[148:151] offset:256
	v_and_b32_e32 v164, 0xffff0000, v179
	v_fmac_f32_e32 v164, v111, v79
	v_lshlrev_b32_e32 v148, 16, v176
	v_and_b32_e32 v149, 0xffff0000, v176
	v_fmac_f32_e32 v148, v112, v80
	v_fmac_f32_e32 v149, v113, v81
	v_cvt_pk_bf16_f32 v148, v148, v149
	v_lshlrev_b32_e32 v149, 16, v177
	v_and_b32_e32 v150, 0xffff0000, v177
	v_fmac_f32_e32 v149, v114, v82
	v_fmac_f32_e32 v150, v115, v83
	v_cvt_pk_bf16_f32 v149, v149, v150
	v_lshlrev_b32_e32 v150, 16, v178
	v_and_b32_e32 v151, 0xffff0000, v178
	v_fmac_f32_e32 v150, v108, v76
	v_fmac_f32_e32 v151, v109, v77
	v_cvt_pk_bf16_f32 v150, v150, v151
	v_lshlrev_b32_e32 v151, 16, v179
	v_fmac_f32_e32 v151, v110, v78
	v_cvt_pk_bf16_f32 v151, v151, v164
	v_lshl_add_u64 v[164:165], s[14:15], 0, v[208:209]
	v_lshl_add_u64 v[164:165], v[164:165], 0, v[190:191]
	flat_store_dwordx4 v[164:165], v[148:151]
	s_nop 1
	v_lshlrev_b32_e32 v148, 16, v160
	v_and_b32_e32 v149, 0xffff0000, v160
	v_fmac_f32_e32 v148, v96, v64
	v_fmac_f32_e32 v149, v97, v65
	v_cvt_pk_bf16_f32 v148, v148, v149
	v_lshlrev_b32_e32 v149, 16, v161
	v_and_b32_e32 v150, 0xffff0000, v161
	v_fmac_f32_e32 v149, v98, v66
	v_fmac_f32_e32 v150, v99, v67
	v_cvt_pk_bf16_f32 v149, v149, v150
	v_lshlrev_b32_e32 v150, 16, v162
	v_and_b32_e32 v151, 0xffff0000, v162
	v_fmac_f32_e32 v150, v92, v60
	v_fmac_f32_e32 v151, v93, v61
	v_cvt_pk_bf16_f32 v150, v150, v151
	v_lshlrev_b32_e32 v151, 16, v163
	v_fmac_f32_e32 v151, v94, v62
	v_and_b32_e32 v160, 0xffff0000, v163
	v_fmac_f32_e32 v160, v95, v63
	v_cvt_pk_bf16_f32 v151, v151, v160
	flat_store_dwordx4 v[164:165], v[148:151] offset:256
	s_nop 1
; __device__ __forceinline__ unsigned cvt_pk_bf16(float lo, float hi) { unsigned r; asm volatile("v_cvt_pk_bf16_f32 %0, %1, %2" : "=v"(r) : "v"(lo), "v"(hi)); return r; }
;     __device__ __forceinline__ void operator()(const f32x4 (&acc)[2][2][4][2], const Unit& u, int wr, int wc, int fr, int fq) const {
;     ...
;             for (int ai = 0; ai < 2; ++ai) { u32x4 bs[4][2];
; #pragma unroll
;                 for (int m = 0; m < 4; ++m) { const size_t off = (size_t)(row0 + ai * HALF + m * 16) * ldc + col0;
; #pragma unroll
;                     for (int bj = 0; bj < 2; ++bj) bs[m][bj] = *(const u32x4*)(bp + off + bj * HALF); }
; #pragma unroll
;                 for (int m = 0; m < 4; ++m) { const size_t off = (size_t)(row0 + ai * HALF + m * 16) * ldc + col0;
; #pragma unroll
;                     for (int bj = 0; bj < 2; ++bj) { const u32x4 r = bs[m][bj]; const f32x4 a0 = acc[ai][bj][m][0], a1 = acc[ai][bj][m][1];
;                         u32x4 w;
;                         w.x = cvt_pk_bf16(__builtin_bit_cast(float, r.x << 16) + gv[bj][0][0] * a0[0], __builtin_bit_cast(float, r.x & 0xffff0000u) + gv[bj][0][1] * a0[1]);
;                         w.y = cvt_pk_bf16(__builtin_bit_cast(float, r.y << 16) + gv[bj][0][2] * a0[2], __builtin_bit_cast(float, r.y & 0xffff0000u) + gv[bj][0][3] * a0[3]);
;                         w.z = cvt_pk_bf16(__builtin_bit_cast(float, r.z << 16) + gv[bj][1][0] * a1[0], __builtin_bit_cast(float, r.z & 0xffff0000u) + gv[bj][1][1] * a1[1]);
;                         w.w = cvt_pk_bf16(__builtin_bit_cast(float, r.w << 16) + gv[bj][1][2] * a1[2], __builtin_bit_cast(float, r.w & 0xffff0000u) + gv[bj][1][3] * a1[3]);
;                         *(u32x4*)(out + off + bj * HALF) = w; } }
;                 asm volatile("" ::: "memory"); }
	v_lshlrev_b32_e32 v148, 16, v156
	v_and_b32_e32 v149, 0xffff0000, v156
	v_fmac_f32_e32 v148, v104, v80
	v_fmac_f32_e32 v149, v105, v81
	v_cvt_pk_bf16_f32 v148, v148, v149
	v_lshlrev_b32_e32 v149, 16, v157
	v_and_b32_e32 v150, 0xffff0000, v157
	v_fmac_f32_e32 v149, v106, v82
	v_fmac_f32_e32 v150, v107, v83
	v_cvt_pk_bf16_f32 v149, v149, v150
	v_lshlrev_b32_e32 v150, 16, v158
	v_and_b32_e32 v151, 0xffff0000, v158
	v_fmac_f32_e32 v150, v100, v76
	v_fmac_f32_e32 v151, v101, v77
	v_cvt_pk_bf16_f32 v150, v150, v151
	v_lshlrev_b32_e32 v151, 16, v159
	v_and_b32_e32 v156, 0xffff0000, v159
	v_fmac_f32_e32 v151, v102, v78
	v_fmac_f32_e32 v156, v103, v79
	v_cvt_pk_bf16_f32 v151, v151, v156
	v_lshl_add_u64 v[156:157], s[14:15], 0, v[206:207]
	v_lshl_add_u64 v[156:157], v[156:157], 0, v[190:191]
	flat_store_dwordx4 v[156:157], v[148:151]
	s_nop 1
	v_lshlrev_b32_e32 v148, 16, v152
	v_and_b32_e32 v149, 0xffff0000, v152
	v_fmac_f32_e32 v148, v88, v64
	v_fmac_f32_e32 v149, v89, v65
	v_cvt_pk_bf16_f32 v148, v148, v149
	v_lshlrev_b32_e32 v149, 16, v153
	v_and_b32_e32 v150, 0xffff0000, v153
	v_fmac_f32_e32 v149, v90, v66
	v_fmac_f32_e32 v150, v91, v67
	v_cvt_pk_bf16_f32 v149, v149, v150
	v_lshlrev_b32_e32 v150, 16, v154
	v_and_b32_e32 v151, 0xffff0000, v154
	v_fmac_f32_e32 v150, v84, v60
	v_fmac_f32_e32 v151, v85, v61
	v_cvt_pk_bf16_f32 v150, v150, v151
	v_lshlrev_b32_e32 v151, 16, v155
	v_fmac_f32_e32 v151, v86, v62
	v_and_b32_e32 v152, 0xffff0000, v155
	v_fmac_f32_e32 v152, v87, v63
	v_cvt_pk_bf16_f32 v151, v151, v152
	flat_store_dwordx4 v[156:157], v[148:151] offset:256
	s_nop 1
	v_lshlrev_b64 v[148:149], 12, v[192:193]
	v_lshl_add_u64 v[206:207], v[148:149], 0, s[12:13]
	v_lshl_add_u64 v[150:151], v[204:205], 0, v[206:207]
	flat_load_dwordx4 v[152:155], v[150:151]
	flat_load_dwordx4 v[156:159], v[150:151] offset:256
	s_mov_b64 s[12:13], 0x90000
	v_lshl_add_u64 v[208:209], v[148:149], 0, s[12:13]
	v_lshl_add_u64 v[150:151], v[204:205], 0, v[208:209]
	flat_load_dwordx4 v[160:163], v[150:151]
	flat_load_dwordx4 v[164:167], v[150:151] offset:256
	s_mov_b64 s[12:13], 0xa0000
	v_lshl_add_u64 v[210:211], v[148:149], 0, s[12:13]
	v_lshl_add_u64 v[150:151], v[204:205], 0, v[210:211]
	flat_load_dwordx4 v[168:171], v[150:151]
	flat_load_dwordx4 v[172:175], v[150:151] offset:256
	s_mov_b64 s[12:13], 0xb0000
	v_lshl_add_u64 v[214:215], v[148:149], 0, s[12:13]
	v_lshl_add_u64 v[148:149], v[204:205], 0, v[214:215]
	flat_load_dwordx4 v[176:179], v[148:149]
	s_nop 0
	flat_load_dwordx4 v[148:151], v[148:149] offset:256
	v_lshl_add_u64 v[204:205], s[14:15], 0, v[206:207]
	v_lshl_add_u64 v[204:205], v[204:205], 0, v[190:191]
	s_waitcnt vmcnt(0) lgkmcnt(0)
; __device__ __forceinline__ unsigned cvt_pk_bf16(float lo, float hi) { unsigned r; asm volatile("v_cvt_pk_bf16_f32 %0, %1, %2" : "=v"(r) : "v"(lo), "v"(hi)); return r; }
;     __device__ __forceinline__ void operator()(const f32x4 (&acc)[2][2][4][2], const Unit& u, int wr, int wc, int fr, int fq) const {
;     ...
;                 for (int m = 0; m < 4; ++m) { const size_t off = (size_t)(row0 + ai * HALF + m * 16) * ldc + col0;
; #pragma unroll
;                     for (int bj = 0; bj < 2; ++bj) { const u32x4 r = bs[m][bj]; const f32x4 a0 = acc[ai][bj][m][0], a1 = acc[ai][bj][m][1];
;                         u32x4 w;
;                         w.x = cvt_pk_bf16(__builtin_bit_cast(float, r.x << 16) + gv[bj][0][0] * a0[0], __builtin_bit_cast(float, r.x & 0xffff0000u) + gv[bj][0][1] * a0[1]);
;                         w.y = cvt_pk_bf16(__builtin_bit_cast(float, r.y << 16) + gv[bj][0][2] * a0[2], __builtin_bit_cast(float, r.y & 0xffff0000u) + gv[bj][0][3] * a0[3]);
;                         w.z = cvt_pk_bf16(__builtin_bit_cast(float, r.z << 16) + gv[bj][1][0] * a1[0], __builtin_bit_cast(float, r.z & 0xffff0000u) + gv[bj][1][1] * a1[1]);
;                         w.w = cvt_pk_bf16(__builtin_bit_cast(float, r.w << 16) + gv[bj][1][2] * a1[2], __builtin_bit_cast(float, r.w & 0xffff0000u) + gv[bj][1][3] * a1[3]);
;                         *(u32x4*)(out + off + bj * HALF) = w; } }
;                 asm volatile("" ::: "memory"); }
	v_lshlrev_b32_e32 v193, 16, v152
	v_and_b32_e32 v152, 0xffff0000, v152
	v_fmac_f32_e32 v193, v72, v80
	v_fmac_f32_e32 v152, v73, v81
	v_cvt_pk_bf16_f32 v152, v193, v152
	v_lshlrev_b32_e32 v193, 16, v153
	v_and_b32_e32 v153, 0xffff0000, v153
	v_fmac_f32_e32 v193, v74, v82
	v_fmac_f32_e32 v153, v75, v83
	v_cvt_pk_bf16_f32 v153, v193, v153
	v_lshlrev_b32_e32 v193, 16, v154
	v_and_b32_e32 v154, 0xffff0000, v154
	v_fmac_f32_e32 v193, v68, v76
	v_fmac_f32_e32 v154, v69, v77
	v_cvt_pk_bf16_f32 v154, v193, v154
	v_lshlrev_b32_e32 v193, 16, v155
	v_and_b32_e32 v155, 0xffff0000, v155
	v_fmac_f32_e32 v155, v71, v79
	v_fmac_f32_e32 v193, v70, v78
	v_cvt_pk_bf16_f32 v155, v193, v155
	flat_store_dwordx4 v[204:205], v[152:155]
	s_nop 1
	v_lshlrev_b32_e32 v152, 16, v156
	v_and_b32_e32 v153, 0xffff0000, v156
	v_fmac_f32_e32 v152, v48, v64
	v_fmac_f32_e32 v153, v49, v65
	v_cvt_pk_bf16_f32 v152, v152, v153
	v_lshlrev_b32_e32 v153, 16, v157
	v_and_b32_e32 v154, 0xffff0000, v157
	v_fmac_f32_e32 v153, v50, v66
	v_fmac_f32_e32 v154, v51, v67
	v_cvt_pk_bf16_f32 v153, v153, v154
	v_lshlrev_b32_e32 v154, 16, v158
	v_and_b32_e32 v155, 0xffff0000, v158
	v_fmac_f32_e32 v154, v44, v60
	v_fmac_f32_e32 v155, v45, v61
	v_cvt_pk_bf16_f32 v154, v154, v155
	v_lshlrev_b32_e32 v155, 16, v159
	v_fmac_f32_e32 v155, v46, v62
	v_and_b32_e32 v156, 0xffff0000, v159
	v_fmac_f32_e32 v156, v47, v63
	v_cvt_pk_bf16_f32 v155, v155, v156
	flat_store_dwordx4 v[204:205], v[152:155] offset:256
	v_and_b32_e32 v156, 0xffff0000, v163
	v_fmac_f32_e32 v156, v55, v79
	v_lshlrev_b32_e32 v152, 16, v160
	v_and_b32_e32 v153, 0xffff0000, v160
	v_fmac_f32_e32 v152, v56, v80
	v_fmac_f32_e32 v153, v57, v81
	v_cvt_pk_bf16_f32 v152, v152, v153
	v_lshlrev_b32_e32 v153, 16, v161
	v_and_b32_e32 v154, 0xffff0000, v161
	v_fmac_f32_e32 v153, v58, v82
	v_fmac_f32_e32 v154, v59, v83
	v_cvt_pk_bf16_f32 v153, v153, v154
	v_lshlrev_b32_e32 v154, 16, v162
	v_and_b32_e32 v155, 0xffff0000, v162
	v_fmac_f32_e32 v154, v52, v76
	v_fmac_f32_e32 v155, v53, v77
	v_cvt_pk_bf16_f32 v154, v154, v155
	v_lshlrev_b32_e32 v155, 16, v163
	v_fmac_f32_e32 v155, v54, v78
	v_cvt_pk_bf16_f32 v155, v155, v156
	v_lshl_add_u64 v[156:157], s[14:15], 0, v[208:209]
	v_lshl_add_u64 v[156:157], v[156:157], 0, v[190:191]
	flat_store_dwordx4 v[156:157], v[152:155]
	v_and_b32_e32 v158, 0xffff0000, v167
	v_fmac_f32_e32 v158, v39, v63
	v_lshlrev_b32_e32 v152, 16, v164
	v_and_b32_e32 v153, 0xffff0000, v164
	v_fmac_f32_e32 v152, v40, v64
	v_fmac_f32_e32 v153, v41, v65
	v_cvt_pk_bf16_f32 v152, v152, v153
	v_lshlrev_b32_e32 v153, 16, v165
	v_and_b32_e32 v154, 0xffff0000, v165
	v_fmac_f32_e32 v153, v42, v66
	v_fmac_f32_e32 v154, v43, v67
	v_cvt_pk_bf16_f32 v153, v153, v154
	v_lshlrev_b32_e32 v154, 16, v166
	v_and_b32_e32 v155, 0xffff0000, v166
	v_fmac_f32_e32 v154, v36, v60
	v_fmac_f32_e32 v155, v37, v61
	v_cvt_pk_bf16_f32 v154, v154, v155
	v_lshlrev_b32_e32 v155, 16, v167
	v_fmac_f32_e32 v155, v38, v62
	v_cvt_pk_bf16_f32 v155, v155, v158
	flat_store_dwordx4 v[156:157], v[152:155] offset:256
	v_and_b32_e32 v156, 0xffff0000, v171
	v_fmac_f32_e32 v156, v31, v79
	v_lshlrev_b32_e32 v152, 16, v168
	v_and_b32_e32 v153, 0xffff0000, v168
	v_fmac_f32_e32 v152, v32, v80
	v_fmac_f32_e32 v153, v33, v81
	v_cvt_pk_bf16_f32 v152, v152, v153
	v_lshlrev_b32_e32 v153, 16, v169
	v_and_b32_e32 v154, 0xffff0000, v169
	v_fmac_f32_e32 v153, v34, v82
	v_fmac_f32_e32 v154, v35, v83
	v_cvt_pk_bf16_f32 v153, v153, v154
	v_lshlrev_b32_e32 v154, 16, v170
	v_and_b32_e32 v155, 0xffff0000, v170
	v_fmac_f32_e32 v154, v28, v76
	v_fmac_f32_e32 v155, v29, v77
	v_cvt_pk_bf16_f32 v154, v154, v155
	v_lshlrev_b32_e32 v155, 16, v171
	v_fmac_f32_e32 v155, v30, v78
	v_cvt_pk_bf16_f32 v155, v155, v156
	v_lshl_add_u64 v[156:157], s[14:15], 0, v[210:211]
	v_lshl_add_u64 v[156:157], v[156:157], 0, v[190:191]
	flat_store_dwordx4 v[156:157], v[152:155]
	v_and_b32_e32 v158, 0xffff0000, v175
	v_fmac_f32_e32 v158, v15, v63
	v_lshlrev_b32_e32 v152, 16, v172
	v_and_b32_e32 v153, 0xffff0000, v172
	v_fmac_f32_e32 v152, v16, v64
	v_fmac_f32_e32 v153, v17, v65
	v_cvt_pk_bf16_f32 v152, v152, v153
	v_lshlrev_b32_e32 v153, 16, v173
	v_and_b32_e32 v154, 0xffff0000, v173
	v_fmac_f32_e32 v153, v18, v66
	v_fmac_f32_e32 v154, v19, v67
	v_cvt_pk_bf16_f32 v153, v153, v154
	v_lshlrev_b32_e32 v154, 16, v174
	v_and_b32_e32 v155, 0xffff0000, v174
	v_fmac_f32_e32 v154, v12, v60
	v_fmac_f32_e32 v155, v13, v61
	v_cvt_pk_bf16_f32 v154, v154, v155
	v_lshlrev_b32_e32 v155, 16, v175
	v_fmac_f32_e32 v155, v14, v62
	v_cvt_pk_bf16_f32 v155, v155, v158
	flat_store_dwordx4 v[156:157], v[152:155] offset:256
	v_and_b32_e32 v156, 0xffff0000, v179
	v_fmac_f32_e32 v156, v23, v79
	v_lshlrev_b32_e32 v152, 16, v176
	v_and_b32_e32 v153, 0xffff0000, v176
	v_fmac_f32_e32 v152, v24, v80
	v_fmac_f32_e32 v153, v25, v81
	v_cvt_pk_bf16_f32 v152, v152, v153
	v_lshlrev_b32_e32 v153, 16, v177
	v_and_b32_e32 v154, 0xffff0000, v177
	v_fmac_f32_e32 v153, v26, v82
	v_fmac_f32_e32 v154, v27, v83
	v_cvt_pk_bf16_f32 v153, v153, v154
	v_lshlrev_b32_e32 v154, 16, v178
	v_and_b32_e32 v155, 0xffff0000, v178
	v_fmac_f32_e32 v154, v20, v76
	v_fmac_f32_e32 v155, v21, v77
	v_cvt_pk_bf16_f32 v154, v154, v155
	v_lshlrev_b32_e32 v155, 16, v179
	v_fmac_f32_e32 v155, v22, v78
	v_cvt_pk_bf16_f32 v155, v155, v156
	v_lshl_add_u64 v[156:157], s[14:15], 0, v[214:215]
	v_lshl_add_u64 v[156:157], v[156:157], 0, v[190:191]
	flat_store_dwordx4 v[156:157], v[152:155]
	s_nop 1
	v_lshlrev_b32_e32 v152, 16, v148
	v_and_b32_e32 v148, 0xffff0000, v148
	v_fmac_f32_e32 v152, v8, v64
	v_fmac_f32_e32 v148, v9, v65
	v_cvt_pk_bf16_f32 v148, v152, v148
	v_lshlrev_b32_e32 v152, 16, v149
	v_and_b32_e32 v149, 0xffff0000, v149
	v_fmac_f32_e32 v152, v10, v66
	v_fmac_f32_e32 v149, v11, v67
	v_cvt_pk_bf16_f32 v149, v152, v149
	v_lshlrev_b32_e32 v152, 16, v150
	v_and_b32_e32 v150, 0xffff0000, v150
	v_fmac_f32_e32 v152, v4, v60
	v_fmac_f32_e32 v150, v5, v61
	v_cvt_pk_bf16_f32 v150, v152, v150
	v_lshlrev_b32_e32 v152, 16, v151
	v_and_b32_e32 v151, 0xffff0000, v151
	v_fmac_f32_e32 v151, v7, v63
	v_fmac_f32_e32 v152, v6, v62
	v_cvt_pk_bf16_f32 v151, v152, v151
	flat_store_dwordx4 v[156:157], v[148:151] offset:256
	s_cbranch_execnz .LBB0_2038
	s_branch .LBB0_2050

; #define PG8_STAGE(bufoff, gbase, voff) do { _Pragma("unroll") for (int _i = 0; _i < 2; ++_i) \
;         __builtin_amdgcn_global_load_lds((const unsigned*)((const char*)(gbase) + (voff)[_i]), (PG8_LAS unsigned*)(lds + (bufoff) + ldsw + _i * 8192), 16, 0, 0); } while (0)
; #define PG8_LDA(dst, b, h) do { _Pragma("unroll") for (int m = 0; m < 4; ++m) _Pragma("unroll") for (int k = 0; k < 2; ++k) dst[m][k] = *(const PG8_LAS bf16x8*)(lds + PG8_SA(b, h) + aoff + m * 2048 + k * 1024); } while (0)
; #define PG8_LDB(dst, b, h) do { _Pragma("unroll") for (int n = 0; n < 2; ++n) _Pragma("unroll") for (int k = 0; k < 2; ++k) dst[n][k] = *(const PG8_LAS bf16x8*)(lds + PG8_SB(b, h) + boff + n * 2048 + k * 1024); } while (0)
; template <class Epi, class Sched, bool ALIGN_EPI = false, bool SP2 = false>
; __device__ __forceinline__ void gemm_phase(PG8_LAS unsigned char* lds, const Gemm g, const Sched& S, const Epi& E) {
;     ...
;         for (int t = 0; t < nt; t += 2) {
;             const bool last = (t == nt - 2);
;             const char* a1 = cA + (size_t)(t + 1) * kstep;
;             const char* a2 = last ? nA : cA + (size_t)(t + 2) * kstep; const char* b2 = last ? nB : cB + (size_t)(t + 2) * kstep;
;             const char* a3 = a2 + kstep; const char* b3 = b2 + kstep;
;             if (last && has_next) S.a_ready(nxt);
;             if constexpr (SP2) {
;             PG8_LDB(B0, 0, 0); PG8_LDB(B1, 0, 1); PG8_SCHED; PG8_LDA(At, 0, 0); PG8_STAGE(PG8_SA(1, 1), a1 + hstep, voffA);
;             PG8_WAIT_V(8); PG8_WAIT_L(0); PG8_BAR; PG8_MMA(0, 0, At, B0); PG8_MMA(0, 1, At, B1); PG8_BAR; PG8_SCHED;
;             PG8_LDA(At, 0, 1); PG8_STAGE(PG8_SB(0, 0), b2, voffB); PG8_STAGE(PG8_SB(0, 1), b2 + hstep, voffB); PG8_STAGE(PG8_SA(0, 0), a2, voffA);
;             PG8_WAIT_V(8); PG8_WAIT_L(0); PG8_BAR; PG8_MMA(1, 0, At, B0); PG8_MMA(1, 1, At, B1); PG8_BAR; PG8_SCHED;
;             PG8_LDB(B0, 1, 0); PG8_LDB(B1, 1, 1); PG8_SCHED; PG8_LDA(At, 1, 0); PG8_STAGE(PG8_SA(0, 1), a2 + hstep, voffA);
;             PG8_WAIT_V(8); PG8_WAIT_L(0); PG8_BAR; PG8_MMA(0, 0, At, B0); PG8_MMA(0, 1, At, B1); PG8_BAR; PG8_SCHED;
;             PG8_LDA(At, 1, 1); PG8_STAGE(PG8_SB(1, 0), b3, voffB); PG8_STAGE(PG8_SB(1, 1), b3 + hstep, voffB); PG8_STAGE(PG8_SA(1, 0), a3, voffA);
;             PG8_WAIT_V(8); PG8_WAIT_L(0); PG8_BAR; PG8_MMA(1, 0, At, B0); PG8_MMA(1, 1, At, B1); PG8_BAR; PG8_SCHED;
.LBB0_2165:
	s_add_u32 s20, s44, 0xfff80080
	s_addc_u32 s21, s45, -1
	s_add_i32 s30, 0, 0x10000
	s_cmp_eq_u32 s56, 28
	s_cselect_b32 s47, s12, s21
	s_cselect_b32 s46, s13, s20
	v_add_u32_e32 v149, s30, v146
	s_cselect_b32 s21, s25, s55
	s_cselect_b32 s20, s27, s33
	s_add_i32 s57, 0, 0x14000
	ds_read_b128 v[142:145], v149
	ds_read_b128 v[150:153], v149 offset:1024
	ds_read_b128 v[154:157], v149 offset:2048
	ds_read_b128 v[158:161], v149 offset:3072
	v_add_u32_e32 v149, s57, v146
	ds_read_b128 v[162:165], v149
	ds_read_b128 v[166:169], v149 offset:1024
	ds_read_b128 v[170:173], v149 offset:2048
	ds_read_b128 v[174:177], v149 offset:3072
	v_lshl_add_u64 v[210:211], s[44:45], 0, v[140:141]
	s_add_i32 m0, s43, 0xc000
	ds_read_b128 v[178:181], v148
	ds_read_b128 v[182:185], v148 offset:1024
	ds_read_b128 v[186:189], v148 offset:2048
	ds_read_b128 v[190:193], v148 offset:3072
	ds_read_b128 v[194:197], v148 offset:4096
	ds_read_b128 v[198:201], v148 offset:5120
	ds_read_b128 v[202:205], v148 offset:6144
	ds_read_b128 v[206:209], v148 offset:7168
	global_load_lds_dwordx4 v[210:211], off
	v_lshl_add_u64 v[210:211], s[44:45], 0, v[138:139]
	s_add_i32 m0, s43, 0xe000
	s_nop 0
	global_load_lds_dwordx4 v[210:211], off
	s_waitcnt vmcnt(8)
	s_waitcnt lgkmcnt(0)
	s_barrier
	s_setprio 1
	s_waitcnt lgkmcnt(0)
	v_mfma_f32_16x16x32_bf16 v[128:131], v[142:145], v[178:181], v[128:131]
	v_mfma_f32_16x16x32_bf16 v[120:123], v[154:157], v[178:181], v[120:123]
	v_mfma_f32_16x16x32_bf16 v[104:107], v[154:157], v[186:189], v[104:107]
	v_mfma_f32_16x16x32_bf16 v[112:115], v[142:145], v[186:189], v[112:115]
	v_mfma_f32_16x16x32_bf16 v[96:99], v[142:145], v[194:197], v[96:99]
	v_mfma_f32_16x16x32_bf16 v[88:91], v[154:157], v[194:197], v[88:91]
	v_mfma_f32_16x16x32_bf16 v[72:75], v[154:157], v[202:205], v[72:75]
	v_mfma_f32_16x16x32_bf16 v[80:83], v[142:145], v[202:205], v[80:83]
	v_mfma_f32_16x16x32_bf16 v[128:131], v[150:153], v[182:185], v[128:131]
	v_mfma_f32_16x16x32_bf16 v[120:123], v[158:161], v[182:185], v[120:123]
	v_mfma_f32_16x16x32_bf16 v[104:107], v[158:161], v[190:193], v[104:107]
	v_mfma_f32_16x16x32_bf16 v[112:115], v[150:153], v[190:193], v[112:115]
	v_mfma_f32_16x16x32_bf16 v[96:99], v[150:153], v[198:201], v[96:99]
	v_mfma_f32_16x16x32_bf16 v[88:91], v[158:161], v[198:201], v[88:91]
	v_mfma_f32_16x16x32_bf16 v[72:75], v[158:161], v[206:209], v[72:75]
	v_mfma_f32_16x16x32_bf16 v[80:83], v[150:153], v[206:209], v[80:83]
	s_setprio 0
	s_setprio 1
	v_mfma_f32_16x16x32_bf16 v[124:127], v[162:165], v[178:181], v[124:127]
	v_mfma_f32_16x16x32_bf16 v[116:119], v[170:173], v[178:181], v[116:119]
	v_mfma_f32_16x16x32_bf16 v[100:103], v[170:173], v[186:189], v[100:103]
	v_mfma_f32_16x16x32_bf16 v[108:111], v[162:165], v[186:189], v[108:111]
	v_mfma_f32_16x16x32_bf16 v[92:95], v[162:165], v[194:197], v[92:95]
	v_mfma_f32_16x16x32_bf16 v[84:87], v[170:173], v[194:197], v[84:87]
	v_mfma_f32_16x16x32_bf16 v[68:71], v[170:173], v[202:205], v[68:71]
	v_mfma_f32_16x16x32_bf16 v[76:79], v[162:165], v[202:205], v[76:79]
	v_mfma_f32_16x16x32_bf16 v[124:127], v[166:169], v[182:185], v[124:127]
	v_mfma_f32_16x16x32_bf16 v[116:119], v[174:177], v[182:185], v[116:119]
	v_mfma_f32_16x16x32_bf16 v[100:103], v[174:177], v[190:193], v[100:103]
	v_mfma_f32_16x16x32_bf16 v[108:111], v[166:169], v[190:193], v[108:111]
	v_mfma_f32_16x16x32_bf16 v[92:95], v[166:169], v[198:201], v[92:95]
	v_mfma_f32_16x16x32_bf16 v[84:87], v[174:177], v[198:201], v[84:87]
	v_mfma_f32_16x16x32_bf16 v[68:71], v[174:177], v[206:209], v[68:71]
	v_mfma_f32_16x16x32_bf16 v[76:79], v[166:169], v[206:209], v[76:79]
	s_setprio 0
	s_barrier
	s_add_i32 s30, s30, s11
	v_lshl_add_u64 v[210:211], s[20:21], 0, v[2:3]
	s_mov_b32 m0, s30
	ds_read_b128 v[178:181], v148 offset:16384
	ds_read_b128 v[182:185], v148 offset:17408
	ds_read_b128 v[186:189], v148 offset:18432
	ds_read_b128 v[190:193], v148 offset:19456
	ds_read_b128 v[194:197], v148 offset:20480
	ds_read_b128 v[198:201], v148 offset:21504
	ds_read_b128 v[202:205], v148 offset:22528
	ds_read_b128 v[206:209], v148 offset:23552
	global_load_lds_dwordx4 v[210:211], off
	s_add_i32 m0, s30, 0x2000
	s_add_u32 s30, s20, 0x80000
	v_lshl_add_u64 v[212:213], s[20:21], 0, v[132:133]
	s_addc_u32 s31, s21, 0
	s_add_i32 s57, s57, s11
	global_load_lds_dwordx4 v[212:213], off
	v_lshl_add_u64 v[214:215], s[30:31], 0, v[2:3]
	s_mov_b32 m0, s57
	v_lshl_add_u64 v[216:217], s[46:47], 0, v[134:135]
	global_load_lds_dwordx4 v[214:215], off
	v_lshl_add_u64 v[214:215], s[30:31], 0, v[132:133]
	s_add_i32 m0, s57, 0x2000
	s_nop 0
	global_load_lds_dwordx4 v[214:215], off
	v_lshl_add_u64 v[214:215], s[46:47], 0, v[136:137]
	s_mov_b32 m0, s43
	s_nop 0
	global_load_lds_dwordx4 v[214:215], off
	s_mov_b32 m0, s49
	s_nop 0
	global_load_lds_dwordx4 v[216:217], off
	s_waitcnt vmcnt(8)
	s_waitcnt lgkmcnt(0)
	s_barrier
; #define PG8_STAGE(bufoff, gbase, voff) do { _Pragma("unroll") for (int _i = 0; _i < 2; ++_i) \
;         __builtin_amdgcn_global_load_lds((const unsigned*)((const char*)(gbase) + (voff)[_i]), (PG8_LAS unsigned*)(lds + (bufoff) + ldsw + _i * 8192), 16, 0, 0); } while (0)
; #define PG8_LDA(dst, b, h) do { _Pragma("unroll") for (int m = 0; m < 4; ++m) _Pragma("unroll") for (int k = 0; k < 2; ++k) dst[m][k] = *(const PG8_LAS bf16x8*)(lds + PG8_SA(b, h) + aoff + m * 2048 + k * 1024); } while (0)
; #define PG8_LDB(dst, b, h) do { _Pragma("unroll") for (int n = 0; n < 2; ++n) _Pragma("unroll") for (int k = 0; k < 2; ++k) dst[n][k] = *(const PG8_LAS bf16x8*)(lds + PG8_SB(b, h) + boff + n * 2048 + k * 1024); } while (0)
; #define PG8_MMA(ai, bj, At, Bt) do { __builtin_amdgcn_s_setprio(1); _Pragma("unroll") for (int m = 0; m < 4; ++m) _Pragma("unroll") for (int n = 0; n < 2; ++n) _Pragma("unroll") for (int k = 0; k < 2; ++k) \
;         acc[ai][bj][m][n] = __builtin_amdgcn_mfma_f32_16x16x32_bf16(Bt[n][k], At[m][k], acc[ai][bj][m][n], 0, 0, 0); __builtin_amdgcn_s_setprio(0); } while (0)
; #define PG8_WAIT_V(n) asm volatile("s_waitcnt vmcnt(" #n ")" ::: "memory")
; template <class Epi, class Sched, bool ALIGN_EPI = false, bool SP2 = false>
; __device__ __forceinline__ void gemm_phase(PG8_LAS unsigned char* lds, const Gemm g, const Sched& S, const Epi& E) {
;     ...
;             PG8_LDB(B0, 0, 0); PG8_LDB(B1, 0, 1); PG8_SCHED; PG8_LDA(At, 0, 0); PG8_STAGE(PG8_SA(1, 1), a1 + hstep, voffA);
;             PG8_WAIT_V(8); PG8_WAIT_L(0); PG8_BAR; PG8_MMA(0, 0, At, B0); PG8_MMA(0, 1, At, B1); PG8_BAR; PG8_SCHED;
;             PG8_LDA(At, 0, 1); PG8_STAGE(PG8_SB(0, 0), b2, voffB); PG8_STAGE(PG8_SB(0, 1), b2 + hstep, voffB); PG8_STAGE(PG8_SA(0, 0), a2, voffA);
;             PG8_WAIT_V(8); PG8_WAIT_L(0); PG8_BAR; PG8_MMA(1, 0, At, B0); PG8_MMA(1, 1, At, B1); PG8_BAR; PG8_SCHED;
;             PG8_LDB(B0, 1, 0); PG8_LDB(B1, 1, 1); PG8_SCHED; PG8_LDA(At, 1, 0); PG8_STAGE(PG8_SA(0, 1), a2 + hstep, voffA);
;             PG8_WAIT_V(8); PG8_WAIT_L(0); PG8_BAR; PG8_MMA(0, 0, At, B0); PG8_MMA(0, 1, At, B1); PG8_BAR; PG8_SCHED;
;             PG8_LDA(At, 1, 1); PG8_STAGE(PG8_SB(1, 0), b3, voffB); PG8_STAGE(PG8_SB(1, 1), b3 + hstep, voffB); PG8_STAGE(PG8_SA(1, 0), a3, voffA);
;             PG8_WAIT_V(8); PG8_WAIT_L(0); PG8_BAR; PG8_MMA(1, 0, At, B0); PG8_MMA(1, 1, At, B1); PG8_BAR; PG8_SCHED;
	s_setprio 1
	s_waitcnt lgkmcnt(0)
	v_mfma_f32_16x16x32_bf16 v[64:67], v[142:145], v[178:181], v[64:67]
	v_mfma_f32_16x16x32_bf16 v[56:59], v[154:157], v[178:181], v[56:59]
	v_mfma_f32_16x16x32_bf16 v[40:43], v[154:157], v[186:189], v[40:43]
	v_mfma_f32_16x16x32_bf16 v[48:51], v[142:145], v[186:189], v[48:51]
	v_mfma_f32_16x16x32_bf16 v[32:35], v[142:145], v[194:197], v[32:35]
	v_mfma_f32_16x16x32_bf16 v[24:27], v[154:157], v[194:197], v[24:27]
	v_mfma_f32_16x16x32_bf16 v[8:11], v[154:157], v[202:205], v[8:11]
	v_mfma_f32_16x16x32_bf16 v[16:19], v[142:145], v[202:205], v[16:19]
	v_mfma_f32_16x16x32_bf16 v[64:67], v[150:153], v[182:185], v[64:67]
	v_mfma_f32_16x16x32_bf16 v[56:59], v[158:161], v[182:185], v[56:59]
	v_mfma_f32_16x16x32_bf16 v[40:43], v[158:161], v[190:193], v[40:43]
	v_mfma_f32_16x16x32_bf16 v[48:51], v[150:153], v[190:193], v[48:51]
	v_mfma_f32_16x16x32_bf16 v[32:35], v[150:153], v[198:201], v[32:35]
	v_mfma_f32_16x16x32_bf16 v[24:27], v[158:161], v[198:201], v[24:27]
	v_mfma_f32_16x16x32_bf16 v[8:11], v[158:161], v[206:209], v[8:11]
	v_mfma_f32_16x16x32_bf16 v[16:19], v[150:153], v[206:209], v[16:19]
	s_setprio 0
	s_setprio 1
	v_mfma_f32_16x16x32_bf16 v[60:63], v[162:165], v[178:181], v[60:63]
	v_mfma_f32_16x16x32_bf16 v[52:55], v[170:173], v[178:181], v[52:55]
	v_mfma_f32_16x16x32_bf16 v[36:39], v[170:173], v[186:189], v[36:39]
	v_mfma_f32_16x16x32_bf16 v[44:47], v[162:165], v[186:189], v[44:47]
	v_mfma_f32_16x16x32_bf16 v[28:31], v[162:165], v[194:197], v[28:31]
	v_mfma_f32_16x16x32_bf16 v[20:23], v[170:173], v[194:197], v[20:23]
	v_mfma_f32_16x16x32_bf16 v[4:7], v[170:173], v[202:205], v[4:7]
	v_mfma_f32_16x16x32_bf16 v[12:15], v[162:165], v[202:205], v[12:15]
	v_mfma_f32_16x16x32_bf16 v[60:63], v[166:169], v[182:185], v[60:63]
	v_mfma_f32_16x16x32_bf16 v[52:55], v[174:177], v[182:185], v[52:55]
	v_mfma_f32_16x16x32_bf16 v[36:39], v[174:177], v[190:193], v[36:39]
	v_mfma_f32_16x16x32_bf16 v[44:47], v[166:169], v[190:193], v[44:47]
	v_mfma_f32_16x16x32_bf16 v[28:31], v[166:169], v[198:201], v[28:31]
	v_mfma_f32_16x16x32_bf16 v[20:23], v[174:177], v[198:201], v[20:23]
	v_mfma_f32_16x16x32_bf16 v[4:7], v[174:177], v[206:209], v[4:7]
	v_mfma_f32_16x16x32_bf16 v[12:15], v[166:169], v[206:209], v[12:15]
	s_setprio 0
	s_barrier
	s_add_i32 s57, 0, 0x18000
	v_add_u32_e32 v149, s57, v146
	s_add_i32 s58, 0, 0x1c000
	ds_read_b128 v[142:145], v149
	ds_read_b128 v[150:153], v149 offset:1024
	ds_read_b128 v[154:157], v149 offset:2048
	ds_read_b128 v[158:161], v149 offset:3072
	v_add_u32_e32 v149, s58, v146
	ds_read_b128 v[162:165], v149
	ds_read_b128 v[166:169], v149 offset:1024
	ds_read_b128 v[170:173], v149 offset:2048
	ds_read_b128 v[174:177], v149 offset:3072
	s_add_u32 s30, s46, 0x80000
	s_addc_u32 s31, s47, 0
	s_mov_b32 m0, s50
	v_lshl_add_u64 v[218:219], s[30:31], 0, v[136:137]
	ds_read_b128 v[178:181], v148 offset:32768
	ds_read_b128 v[182:185], v148 offset:33792
	ds_read_b128 v[186:189], v148 offset:34816
	ds_read_b128 v[190:193], v148 offset:35840
	ds_read_b128 v[194:197], v148 offset:36864
	ds_read_b128 v[198:201], v148 offset:37888
	ds_read_b128 v[202:205], v148 offset:38912
	ds_read_b128 v[206:209], v148 offset:39936
	global_load_lds_dwordx4 v[218:219], off
	v_lshl_add_u64 v[218:219], s[30:31], 0, v[134:135]
	s_mov_b32 m0, s51
	s_nop 0
	global_load_lds_dwordx4 v[218:219], off
	s_waitcnt vmcnt(8)
	s_waitcnt lgkmcnt(0)
	s_barrier
	s_setprio 1
	s_waitcnt lgkmcnt(0)
	v_mfma_f32_16x16x32_bf16 v[128:131], v[142:145], v[178:181], v[128:131]
	v_mfma_f32_16x16x32_bf16 v[120:123], v[154:157], v[178:181], v[120:123]
	v_mfma_f32_16x16x32_bf16 v[104:107], v[154:157], v[186:189], v[104:107]
	v_mfma_f32_16x16x32_bf16 v[112:115], v[142:145], v[186:189], v[112:115]
	v_mfma_f32_16x16x32_bf16 v[96:99], v[142:145], v[194:197], v[96:99]
	v_mfma_f32_16x16x32_bf16 v[88:91], v[154:157], v[194:197], v[88:91]
	v_mfma_f32_16x16x32_bf16 v[72:75], v[154:157], v[202:205], v[72:75]
	v_mfma_f32_16x16x32_bf16 v[80:83], v[142:145], v[202:205], v[80:83]
	v_mfma_f32_16x16x32_bf16 v[128:131], v[150:153], v[182:185], v[128:131]
	v_mfma_f32_16x16x32_bf16 v[120:123], v[158:161], v[182:185], v[120:123]
	v_mfma_f32_16x16x32_bf16 v[104:107], v[158:161], v[190:193], v[104:107]
	v_mfma_f32_16x16x32_bf16 v[112:115], v[150:153], v[190:193], v[112:115]
	v_mfma_f32_16x16x32_bf16 v[96:99], v[150:153], v[198:201], v[96:99]
	v_mfma_f32_16x16x32_bf16 v[88:91], v[158:161], v[198:201], v[88:91]
	v_mfma_f32_16x16x32_bf16 v[72:75], v[158:161], v[206:209], v[72:75]
	v_mfma_f32_16x16x32_bf16 v[80:83], v[150:153], v[206:209], v[80:83]
	s_setprio 0
	s_setprio 1
	v_mfma_f32_16x16x32_bf16 v[124:127], v[162:165], v[178:181], v[124:127]
	v_mfma_f32_16x16x32_bf16 v[116:119], v[170:173], v[178:181], v[116:119]
	v_mfma_f32_16x16x32_bf16 v[100:103], v[170:173], v[186:189], v[100:103]
	v_mfma_f32_16x16x32_bf16 v[108:111], v[162:165], v[186:189], v[108:111]
	v_mfma_f32_16x16x32_bf16 v[92:95], v[162:165], v[194:197], v[92:95]
	v_mfma_f32_16x16x32_bf16 v[84:87], v[170:173], v[194:197], v[84:87]
	v_mfma_f32_16x16x32_bf16 v[68:71], v[170:173], v[202:205], v[68:71]
	v_mfma_f32_16x16x32_bf16 v[76:79], v[162:165], v[202:205], v[76:79]
	v_mfma_f32_16x16x32_bf16 v[124:127], v[166:169], v[182:185], v[124:127]
	v_mfma_f32_16x16x32_bf16 v[116:119], v[174:177], v[182:185], v[116:119]
	v_mfma_f32_16x16x32_bf16 v[100:103], v[174:177], v[190:193], v[100:103]
	v_mfma_f32_16x16x32_bf16 v[108:111], v[166:169], v[190:193], v[108:111]
	v_mfma_f32_16x16x32_bf16 v[92:95], v[166:169], v[198:201], v[92:95]
	v_mfma_f32_16x16x32_bf16 v[84:87], v[174:177], v[198:201], v[84:87]
	v_mfma_f32_16x16x32_bf16 v[68:71], v[174:177], v[206:209], v[68:71]
	v_mfma_f32_16x16x32_bf16 v[76:79], v[166:169], v[206:209], v[76:79]
	s_setprio 0
	s_barrier
; #define PG8_STAGE(bufoff, gbase, voff) do { _Pragma("unroll") for (int _i = 0; _i < 2; ++_i) \
;         __builtin_amdgcn_global_load_lds((const unsigned*)((const char*)(gbase) + (voff)[_i]), (PG8_LAS unsigned*)(lds + (bufoff) + ldsw + _i * 8192), 16, 0, 0); } while (0)
; #define PG8_LDA(dst, b, h) do { _Pragma("unroll") for (int m = 0; m < 4; ++m) _Pragma("unroll") for (int k = 0; k < 2; ++k) dst[m][k] = *(const PG8_LAS bf16x8*)(lds + PG8_SA(b, h) + aoff + m * 2048 + k * 1024); } while (0)
; #define PG8_LDB(dst, b, h) do { _Pragma("unroll") for (int n = 0; n < 2; ++n) _Pragma("unroll") for (int k = 0; k < 2; ++k) dst[n][k] = *(const PG8_LAS bf16x8*)(lds + PG8_SB(b, h) + boff + n * 2048 + k * 1024); } while (0)
; #define PG8_MMA(ai, bj, At, Bt) do { __builtin_amdgcn_s_setprio(1); _Pragma("unroll") for (int m = 0; m < 4; ++m) _Pragma("unroll") for (int n = 0; n < 2; ++n) _Pragma("unroll") for (int k = 0; k < 2; ++k) \
;         acc[ai][bj][m][n] = __builtin_amdgcn_mfma_f32_16x16x32_bf16(Bt[n][k], At[m][k], acc[ai][bj][m][n], 0, 0, 0); __builtin_amdgcn_s_setprio(0); } while (0)
; #define PG8_WAIT_V(n) asm volatile("s_waitcnt vmcnt(" #n ")" ::: "memory")
; #define PG8_WAIT_L(n) asm volatile("s_waitcnt lgkmcnt(" #n ")" ::: "memory")
; #define PG8_BAR __builtin_amdgcn_s_barrier()
; #define PG8_SCHED __builtin_amdgcn_sched_barrier(0)
; template <class Epi, class Sched, bool ALIGN_EPI = false, bool SP2 = false>
; __device__ __forceinline__ void gemm_phase(PG8_LAS unsigned char* lds, const Gemm g, const Sched& S, const Epi& E) {
;     ...
;             PG8_LDB(B0, 1, 0); PG8_LDB(B1, 1, 1); PG8_SCHED; PG8_LDA(At, 1, 0); PG8_STAGE(PG8_SA(0, 1), a2 + hstep, voffA);
;             PG8_WAIT_V(8); PG8_WAIT_L(0); PG8_BAR; PG8_MMA(0, 0, At, B0); PG8_MMA(0, 1, At, B1); PG8_BAR; PG8_SCHED;
;             PG8_LDA(At, 1, 1); PG8_STAGE(PG8_SB(1, 0), b3, voffB); PG8_STAGE(PG8_SB(1, 1), b3 + hstep, voffB); PG8_STAGE(PG8_SA(1, 0), a3, voffA);
;             PG8_WAIT_V(8); PG8_WAIT_L(0); PG8_BAR; PG8_MMA(1, 0, At, B0); PG8_MMA(1, 1, At, B1); PG8_BAR; PG8_SCHED;
;     ...
;         }
;         if constexpr (ALIGN_EPI) { if (wr == 0) PG8_BAR; }
	s_add_i32 s30, s57, s11
	v_lshl_add_u64 v[210:211], v[210:211], 0, s[28:29]
	s_mov_b32 m0, s30
	ds_read_b128 v[178:181], v148 offset:49152
	ds_read_b128 v[182:185], v148 offset:50176
	ds_read_b128 v[186:189], v148 offset:51200
	ds_read_b128 v[190:193], v148 offset:52224
	ds_read_b128 v[194:197], v148 offset:53248
	ds_read_b128 v[198:201], v148 offset:54272
	ds_read_b128 v[202:205], v148 offset:55296
	ds_read_b128 v[206:209], v148 offset:56320
	global_load_lds_dwordx4 v[210:211], off
	s_add_i32 m0, s30, 0x2000
	s_add_u32 s20, s20, 0x80080
	v_lshl_add_u64 v[210:211], v[212:213], 0, s[28:29]
	s_addc_u32 s21, s21, 0
	s_add_i32 s30, s58, s11
	global_load_lds_dwordx4 v[210:211], off
	v_lshl_add_u64 v[210:211], s[20:21], 0, v[2:3]
	s_mov_b32 m0, s30
	s_nop 0
	global_load_lds_dwordx4 v[210:211], off
	v_lshl_add_u64 v[210:211], s[20:21], 0, v[132:133]
	s_add_i32 m0, s30, 0x2000
	s_nop 0
	global_load_lds_dwordx4 v[210:211], off
	v_lshl_add_u64 v[210:211], v[214:215], 0, s[28:29]
	s_mov_b32 m0, s18
	s_nop 0
	global_load_lds_dwordx4 v[210:211], off
	v_lshl_add_u64 v[210:211], v[216:217], 0, s[28:29]
	s_mov_b32 m0, s52
	s_nop 0
	global_load_lds_dwordx4 v[210:211], off
	s_waitcnt vmcnt(8)
	s_waitcnt lgkmcnt(0)
	s_barrier
	s_setprio 1
	s_waitcnt lgkmcnt(0)
	v_mfma_f32_16x16x32_bf16 v[64:67], v[142:145], v[178:181], v[64:67]
	v_mfma_f32_16x16x32_bf16 v[56:59], v[154:157], v[178:181], v[56:59]
	v_mfma_f32_16x16x32_bf16 v[40:43], v[154:157], v[186:189], v[40:43]
	v_mfma_f32_16x16x32_bf16 v[48:51], v[142:145], v[186:189], v[48:51]
	v_mfma_f32_16x16x32_bf16 v[32:35], v[142:145], v[194:197], v[32:35]
	v_mfma_f32_16x16x32_bf16 v[24:27], v[154:157], v[194:197], v[24:27]
	v_mfma_f32_16x16x32_bf16 v[8:11], v[154:157], v[202:205], v[8:11]
	v_mfma_f32_16x16x32_bf16 v[16:19], v[142:145], v[202:205], v[16:19]
	v_mfma_f32_16x16x32_bf16 v[64:67], v[150:153], v[182:185], v[64:67]
	v_mfma_f32_16x16x32_bf16 v[56:59], v[158:161], v[182:185], v[56:59]
	v_mfma_f32_16x16x32_bf16 v[40:43], v[158:161], v[190:193], v[40:43]
	v_mfma_f32_16x16x32_bf16 v[48:51], v[150:153], v[190:193], v[48:51]
	v_mfma_f32_16x16x32_bf16 v[32:35], v[150:153], v[198:201], v[32:35]
	v_mfma_f32_16x16x32_bf16 v[24:27], v[158:161], v[198:201], v[24:27]
	v_mfma_f32_16x16x32_bf16 v[8:11], v[158:161], v[206:209], v[8:11]
	v_mfma_f32_16x16x32_bf16 v[16:19], v[150:153], v[206:209], v[16:19]
	s_setprio 0
	s_setprio 1
	v_mfma_f32_16x16x32_bf16 v[60:63], v[162:165], v[178:181], v[60:63]
	v_mfma_f32_16x16x32_bf16 v[52:55], v[170:173], v[178:181], v[52:55]
	v_mfma_f32_16x16x32_bf16 v[36:39], v[170:173], v[186:189], v[36:39]
	v_mfma_f32_16x16x32_bf16 v[44:47], v[162:165], v[186:189], v[44:47]
	v_mfma_f32_16x16x32_bf16 v[28:31], v[162:165], v[194:197], v[28:31]
	v_mfma_f32_16x16x32_bf16 v[20:23], v[170:173], v[194:197], v[20:23]
	v_mfma_f32_16x16x32_bf16 v[4:7], v[170:173], v[202:205], v[4:7]
	v_mfma_f32_16x16x32_bf16 v[12:15], v[162:165], v[202:205], v[12:15]
	v_mfma_f32_16x16x32_bf16 v[60:63], v[166:169], v[182:185], v[60:63]
	v_mfma_f32_16x16x32_bf16 v[52:55], v[174:177], v[182:185], v[52:55]
	v_mfma_f32_16x16x32_bf16 v[36:39], v[174:177], v[190:193], v[36:39]
	v_mfma_f32_16x16x32_bf16 v[44:47], v[166:169], v[190:193], v[44:47]
	v_mfma_f32_16x16x32_bf16 v[28:31], v[166:169], v[198:201], v[28:31]
	v_mfma_f32_16x16x32_bf16 v[20:23], v[174:177], v[198:201], v[20:23]
	v_mfma_f32_16x16x32_bf16 v[4:7], v[174:177], v[206:209], v[4:7]
	v_mfma_f32_16x16x32_bf16 v[12:15], v[166:169], v[206:209], v[12:15]
	s_setprio 0
	s_barrier
	s_add_i32 s56, s56, 2
	s_add_u32 s33, s33, 0x100
	s_addc_u32 s55, s55, 0
	s_add_u32 s44, s44, 0x100
	s_addc_u32 s45, s45, 0
	s_cmp_gt_u32 s56, 29
	s_cbranch_scc0 .LBB0_2165
	s_and_b64 vcc, exec, s[22:23]
	s_cbranch_vccz .LBB0_2168
	s_barrier

; #define PG8_STAGE(bufoff, gbase, voff) do { _Pragma("unroll") for (int _i = 0; _i < 2; ++_i) \
;         __builtin_amdgcn_global_load_lds((const unsigned*)((const char*)(gbase) + (voff)[_i]), (PG8_LAS unsigned*)(lds + (bufoff) + ldsw + _i * 8192), 16, 0, 0); } while (0)
; #define PG8_LDA(dst, b, h) do { _Pragma("unroll") for (int m = 0; m < 4; ++m) _Pragma("unroll") for (int k = 0; k < 2; ++k) dst[m][k] = *(const PG8_LAS bf16x8*)(lds + PG8_SA(b, h) + aoff + m * 2048 + k * 1024); } while (0)
; #define PG8_LDB(dst, b, h) do { _Pragma("unroll") for (int n = 0; n < 2; ++n) _Pragma("unroll") for (int k = 0; k < 2; ++k) dst[n][k] = *(const PG8_LAS bf16x8*)(lds + PG8_SB(b, h) + boff + n * 2048 + k * 1024); } while (0)
; #define PG8_MMA(ai, bj, At, Bt) do { __builtin_amdgcn_s_setprio(1); _Pragma("unroll") for (int m = 0; m < 4; ++m) _Pragma("unroll") for (int n = 0; n < 2; ++n) _Pragma("unroll") for (int k = 0; k < 2; ++k) \
;         acc[ai][bj][m][n] = __builtin_amdgcn_mfma_f32_16x16x32_bf16(Bt[n][k], At[m][k], acc[ai][bj][m][n], 0, 0, 0); __builtin_amdgcn_s_setprio(0); } while (0)
; #define PG8_WAIT_V(n) asm volatile("s_waitcnt vmcnt(" #n ")" ::: "memory")
; #define PG8_BAR __builtin_amdgcn_s_barrier()
; template <class Epi, class Sched, bool ALIGN_EPI = false, bool SP2 = false>
; __device__ __forceinline__ void gemm_phase(PG8_LAS unsigned char* lds, const Gemm g, const Sched& S, const Epi& E) {
;     ...
;         for (int t = 0; t < nt; t += 2) {
;             const bool last = (t == nt - 2);
;             const char* a1 = cA + (size_t)(t + 1) * kstep;
;             const char* a2 = last ? nA : cA + (size_t)(t + 2) * kstep; const char* b2 = last ? nB : cB + (size_t)(t + 2) * kstep;
;             const char* a3 = a2 + kstep; const char* b3 = b2 + kstep;
;             if (last && has_next) S.a_ready(nxt);
;             if constexpr (SP2) {
;             PG8_LDB(B0, 0, 0); PG8_LDB(B1, 0, 1); PG8_SCHED; PG8_LDA(At, 0, 0); PG8_STAGE(PG8_SA(1, 1), a1 + hstep, voffA);
;             PG8_WAIT_V(8); PG8_WAIT_L(0); PG8_BAR; PG8_MMA(0, 0, At, B0); PG8_MMA(0, 1, At, B1); PG8_BAR; PG8_SCHED;
;             PG8_LDA(At, 0, 1); PG8_STAGE(PG8_SB(0, 0), b2, voffB); PG8_STAGE(PG8_SB(0, 1), b2 + hstep, voffB); PG8_STAGE(PG8_SA(0, 0), a2, voffA);
;             PG8_WAIT_V(8); PG8_WAIT_L(0); PG8_BAR; PG8_MMA(1, 0, At, B0); PG8_MMA(1, 1, At, B1); PG8_BAR; PG8_SCHED;
.LBB0_2238:
	s_add_u32 s24, s20, 0x100
	s_addc_u32 s25, s21, 0
	s_add_i32 s30, 0, 0x10000
	s_cmpk_eq_i32 s42, 0x54
	s_cselect_b32 s37, s17, s25
	s_cselect_b32 s36, s16, s24
	s_cselect_b32 s27, s23, s41
	s_cselect_b32 s26, s22, s40
	s_add_i32 s31, 0, 0x14000
	v_add_u32_e32 v136, s30, v198
	v_add_u32_e32 v160, s31, v198
	ds_read_b128 v[124:127], v136
	ds_read_b128 v[128:131], v136 offset:1024
	ds_read_b128 v[132:135], v136 offset:2048
	ds_read_b128 v[136:139], v136 offset:3072
	ds_read_b128 v[148:151], v160
	ds_read_b128 v[152:155], v160 offset:1024
	ds_read_b128 v[156:159], v160 offset:2048
	ds_read_b128 v[160:163], v160 offset:3072
	v_lshl_add_u64 v[210:211], s[20:21], 0, v[184:185]
	s_add_i32 m0, s18, 0xc000
	ds_read_b128 v[164:167], v200
	ds_read_b128 v[168:171], v200 offset:1024
	ds_read_b128 v[172:175], v200 offset:2048
	ds_read_b128 v[186:189], v200 offset:3072
	ds_read_b128 v[190:193], v200 offset:4096
	ds_read_b128 v[194:197], v200 offset:5120
	ds_read_b128 v[202:205], v200 offset:6144
	ds_read_b128 v[206:209], v200 offset:7168
	global_load_lds_dwordx4 v[210:211], off
	v_lshl_add_u64 v[210:211], s[20:21], 0, v[182:183]
	s_add_i32 m0, s18, 0xe000
	s_nop 0
	global_load_lds_dwordx4 v[210:211], off
	s_waitcnt vmcnt(8)
	s_waitcnt lgkmcnt(0)
	s_barrier
	s_setprio 1
	s_waitcnt lgkmcnt(0)
	v_mfma_f32_16x16x32_bf16 v[144:147], v[124:127], v[164:167], v[144:147]
	v_mfma_f32_16x16x32_bf16 v[140:143], v[132:135], v[164:167], v[140:143]
	v_mfma_f32_16x16x32_bf16 v[108:111], v[132:135], v[172:175], v[108:111]
	v_mfma_f32_16x16x32_bf16 v[112:115], v[124:127], v[172:175], v[112:115]
	v_mfma_f32_16x16x32_bf16 v[100:103], v[124:127], v[190:193], v[100:103]
	v_mfma_f32_16x16x32_bf16 v[92:95], v[132:135], v[190:193], v[92:95]
	v_mfma_f32_16x16x32_bf16 v[76:79], v[132:135], v[202:205], v[76:79]
	v_mfma_f32_16x16x32_bf16 v[84:87], v[124:127], v[202:205], v[84:87]
	v_mfma_f32_16x16x32_bf16 v[144:147], v[128:131], v[168:171], v[144:147]
	v_mfma_f32_16x16x32_bf16 v[140:143], v[136:139], v[168:171], v[140:143]
	v_mfma_f32_16x16x32_bf16 v[108:111], v[136:139], v[186:189], v[108:111]
	v_mfma_f32_16x16x32_bf16 v[112:115], v[128:131], v[186:189], v[112:115]
	v_mfma_f32_16x16x32_bf16 v[100:103], v[128:131], v[194:197], v[100:103]
	v_mfma_f32_16x16x32_bf16 v[92:95], v[136:139], v[194:197], v[92:95]
	v_mfma_f32_16x16x32_bf16 v[76:79], v[136:139], v[206:209], v[76:79]
	v_mfma_f32_16x16x32_bf16 v[84:87], v[128:131], v[206:209], v[84:87]
	s_setprio 0
	s_setprio 1
	v_mfma_f32_16x16x32_bf16 v[120:123], v[148:151], v[164:167], v[120:123]
	v_mfma_f32_16x16x32_bf16 v[116:119], v[156:159], v[164:167], v[116:119]
	v_mfma_f32_16x16x32_bf16 v[96:99], v[156:159], v[172:175], v[96:99]
	v_mfma_f32_16x16x32_bf16 v[104:107], v[148:151], v[172:175], v[104:107]
	v_mfma_f32_16x16x32_bf16 v[88:91], v[148:151], v[190:193], v[88:91]
	v_mfma_f32_16x16x32_bf16 v[80:83], v[156:159], v[190:193], v[80:83]
	v_mfma_f32_16x16x32_bf16 v[68:71], v[156:159], v[202:205], v[68:71]
	v_mfma_f32_16x16x32_bf16 v[72:75], v[148:151], v[202:205], v[72:75]
	v_mfma_f32_16x16x32_bf16 v[120:123], v[152:155], v[168:171], v[120:123]
	v_mfma_f32_16x16x32_bf16 v[116:119], v[160:163], v[168:171], v[116:119]
	v_mfma_f32_16x16x32_bf16 v[96:99], v[160:163], v[186:189], v[96:99]
	v_mfma_f32_16x16x32_bf16 v[104:107], v[152:155], v[186:189], v[104:107]
	v_mfma_f32_16x16x32_bf16 v[88:91], v[152:155], v[194:197], v[88:91]
	v_mfma_f32_16x16x32_bf16 v[80:83], v[160:163], v[194:197], v[80:83]
	v_mfma_f32_16x16x32_bf16 v[68:71], v[160:163], v[206:209], v[68:71]
	v_mfma_f32_16x16x32_bf16 v[72:75], v[152:155], v[206:209], v[72:75]
	s_setprio 0
	s_barrier
	s_add_i32 s20, s30, s13
	v_lshl_add_u64 v[210:211], s[26:27], 0, v[2:3]
	s_mov_b32 m0, s20
	ds_read_b128 v[164:167], v200 offset:16384
	ds_read_b128 v[168:171], v200 offset:17408
	ds_read_b128 v[172:175], v200 offset:18432
	ds_read_b128 v[186:189], v200 offset:19456
	ds_read_b128 v[190:193], v200 offset:20480
	ds_read_b128 v[194:197], v200 offset:21504
	ds_read_b128 v[202:205], v200 offset:22528
	ds_read_b128 v[206:209], v200 offset:23552
	global_load_lds_dwordx4 v[210:211], off
	s_add_i32 m0, s20, 0x2000
	s_add_u32 s20, s26, 0x160000
	v_lshl_add_u64 v[212:213], s[26:27], 0, v[180:181]
	s_addc_u32 s21, s27, 0
	s_add_i32 s30, s31, s13
	global_load_lds_dwordx4 v[212:213], off
	v_lshl_add_u64 v[214:215], s[20:21], 0, v[2:3]
	s_mov_b32 m0, s30
	v_lshl_add_u64 v[216:217], s[36:37], 0, v[178:179]
	global_load_lds_dwordx4 v[214:215], off
	v_lshl_add_u64 v[214:215], s[20:21], 0, v[180:181]
	s_add_i32 m0, s30, 0x2000
	s_nop 0
	global_load_lds_dwordx4 v[214:215], off
	v_lshl_add_u64 v[214:215], s[36:37], 0, v[176:177]
	s_mov_b32 m0, s18
	s_nop 0
	global_load_lds_dwordx4 v[214:215], off
	s_mov_b32 m0, s44
	s_nop 0
	global_load_lds_dwordx4 v[216:217], off
	s_waitcnt vmcnt(8)
	s_waitcnt lgkmcnt(0)
	s_barrier
; #define PG8_STAGE(bufoff, gbase, voff) do { _Pragma("unroll") for (int _i = 0; _i < 2; ++_i) \
;         __builtin_amdgcn_global_load_lds((const unsigned*)((const char*)(gbase) + (voff)[_i]), (PG8_LAS unsigned*)(lds + (bufoff) + ldsw + _i * 8192), 16, 0, 0); } while (0)
; #define PG8_LDA(dst, b, h) do { _Pragma("unroll") for (int m = 0; m < 4; ++m) _Pragma("unroll") for (int k = 0; k < 2; ++k) dst[m][k] = *(const PG8_LAS bf16x8*)(lds + PG8_SA(b, h) + aoff + m * 2048 + k * 1024); } while (0)
; #define PG8_LDB(dst, b, h) do { _Pragma("unroll") for (int n = 0; n < 2; ++n) _Pragma("unroll") for (int k = 0; k < 2; ++k) dst[n][k] = *(const PG8_LAS bf16x8*)(lds + PG8_SB(b, h) + boff + n * 2048 + k * 1024); } while (0)
; #define PG8_MMA(ai, bj, At, Bt) do { __builtin_amdgcn_s_setprio(1); _Pragma("unroll") for (int m = 0; m < 4; ++m) _Pragma("unroll") for (int n = 0; n < 2; ++n) _Pragma("unroll") for (int k = 0; k < 2; ++k) \
;         acc[ai][bj][m][n] = __builtin_amdgcn_mfma_f32_16x16x32_bf16(Bt[n][k], At[m][k], acc[ai][bj][m][n], 0, 0, 0); __builtin_amdgcn_s_setprio(0); } while (0)
; #define PG8_WAIT_V(n) asm volatile("s_waitcnt vmcnt(" #n ")" ::: "memory")
; #define PG8_WAIT_L(n) asm volatile("s_waitcnt lgkmcnt(" #n ")" ::: "memory")
; #define PG8_BAR __builtin_amdgcn_s_barrier()
; #define PG8_SCHED __builtin_amdgcn_sched_barrier(0)
; template <class Epi, class Sched, bool ALIGN_EPI = false, bool SP2 = false>
; __device__ __forceinline__ void gemm_phase(PG8_LAS unsigned char* lds, const Gemm g, const Sched& S, const Epi& E) {
;     ...
;             PG8_LDA(At, 0, 1); PG8_STAGE(PG8_SB(0, 0), b2, voffB); PG8_STAGE(PG8_SB(0, 1), b2 + hstep, voffB); PG8_STAGE(PG8_SA(0, 0), a2, voffA);
;             PG8_WAIT_V(8); PG8_WAIT_L(0); PG8_BAR; PG8_MMA(1, 0, At, B0); PG8_MMA(1, 1, At, B1); PG8_BAR; PG8_SCHED;
;             PG8_LDB(B0, 1, 0); PG8_LDB(B1, 1, 1); PG8_SCHED; PG8_LDA(At, 1, 0); PG8_STAGE(PG8_SA(0, 1), a2 + hstep, voffA);
;             PG8_WAIT_V(8); PG8_WAIT_L(0); PG8_BAR; PG8_MMA(0, 0, At, B0); PG8_MMA(0, 1, At, B1); PG8_BAR; PG8_SCHED;
;             PG8_LDA(At, 1, 1); PG8_STAGE(PG8_SB(1, 0), b3, voffB); PG8_STAGE(PG8_SB(1, 1), b3 + hstep, voffB); PG8_STAGE(PG8_SA(1, 0), a3, voffA);
;             PG8_WAIT_V(8); PG8_WAIT_L(0); PG8_BAR; PG8_MMA(1, 0, At, B0); PG8_MMA(1, 1, At, B1); PG8_BAR; PG8_SCHED;
	s_setprio 1
	s_waitcnt lgkmcnt(0)
	v_mfma_f32_16x16x32_bf16 v[64:67], v[124:127], v[164:167], v[64:67]
	v_mfma_f32_16x16x32_bf16 v[60:63], v[132:135], v[164:167], v[60:63]
	v_mfma_f32_16x16x32_bf16 v[44:47], v[132:135], v[172:175], v[44:47]
	v_mfma_f32_16x16x32_bf16 v[52:55], v[124:127], v[172:175], v[52:55]
	v_mfma_f32_16x16x32_bf16 v[36:39], v[124:127], v[190:193], v[36:39]
	v_mfma_f32_16x16x32_bf16 v[28:31], v[132:135], v[190:193], v[28:31]
	v_mfma_f32_16x16x32_bf16 v[12:15], v[132:135], v[202:205], v[12:15]
	v_mfma_f32_16x16x32_bf16 v[20:23], v[124:127], v[202:205], v[20:23]
	v_mfma_f32_16x16x32_bf16 v[64:67], v[128:131], v[168:171], v[64:67]
	v_mfma_f32_16x16x32_bf16 v[60:63], v[136:139], v[168:171], v[60:63]
	v_mfma_f32_16x16x32_bf16 v[44:47], v[136:139], v[186:189], v[44:47]
	v_mfma_f32_16x16x32_bf16 v[52:55], v[128:131], v[186:189], v[52:55]
	v_mfma_f32_16x16x32_bf16 v[36:39], v[128:131], v[194:197], v[36:39]
	v_mfma_f32_16x16x32_bf16 v[28:31], v[136:139], v[194:197], v[28:31]
	v_mfma_f32_16x16x32_bf16 v[12:15], v[136:139], v[206:209], v[12:15]
	v_mfma_f32_16x16x32_bf16 v[20:23], v[128:131], v[206:209], v[20:23]
	s_setprio 0
	s_setprio 1
	v_mfma_f32_16x16x32_bf16 v[56:59], v[148:151], v[164:167], v[56:59]
	v_mfma_f32_16x16x32_bf16 v[48:51], v[156:159], v[164:167], v[48:51]
	v_mfma_f32_16x16x32_bf16 v[32:35], v[156:159], v[172:175], v[32:35]
	v_mfma_f32_16x16x32_bf16 v[40:43], v[148:151], v[172:175], v[40:43]
	v_mfma_f32_16x16x32_bf16 v[24:27], v[148:151], v[190:193], v[24:27]
	v_mfma_f32_16x16x32_bf16 v[16:19], v[156:159], v[190:193], v[16:19]
	v_mfma_f32_16x16x32_bf16 v[4:7], v[156:159], v[202:205], v[4:7]
	v_mfma_f32_16x16x32_bf16 v[8:11], v[148:151], v[202:205], v[8:11]
	v_mfma_f32_16x16x32_bf16 v[56:59], v[152:155], v[168:171], v[56:59]
	v_mfma_f32_16x16x32_bf16 v[48:51], v[160:163], v[168:171], v[48:51]
	v_mfma_f32_16x16x32_bf16 v[32:35], v[160:163], v[186:189], v[32:35]
	v_mfma_f32_16x16x32_bf16 v[40:43], v[152:155], v[186:189], v[40:43]
	v_mfma_f32_16x16x32_bf16 v[24:27], v[152:155], v[194:197], v[24:27]
	v_mfma_f32_16x16x32_bf16 v[16:19], v[160:163], v[194:197], v[16:19]
	v_mfma_f32_16x16x32_bf16 v[4:7], v[160:163], v[206:209], v[4:7]
	v_mfma_f32_16x16x32_bf16 v[8:11], v[152:155], v[206:209], v[8:11]
	s_setprio 0
	s_barrier
	s_add_i32 s30, 0, 0x18000
	s_add_i32 s31, 0, 0x1c000
	v_add_u32_e32 v136, s30, v198
	v_add_u32_e32 v160, s31, v198
	ds_read_b128 v[124:127], v136
	ds_read_b128 v[128:131], v136 offset:1024
	ds_read_b128 v[132:135], v136 offset:2048
	ds_read_b128 v[136:139], v136 offset:3072
	ds_read_b128 v[148:151], v160
	ds_read_b128 v[152:155], v160 offset:1024
	ds_read_b128 v[156:159], v160 offset:2048
	ds_read_b128 v[160:163], v160 offset:3072
	s_add_u32 s20, s36, 0x160000
	s_addc_u32 s21, s37, 0
	s_mov_b32 m0, s45
	v_lshl_add_u64 v[218:219], s[20:21], 0, v[176:177]
	ds_read_b128 v[164:167], v200 offset:32768
	ds_read_b128 v[168:171], v200 offset:33792
	ds_read_b128 v[172:175], v200 offset:34816
	ds_read_b128 v[186:189], v200 offset:35840
	ds_read_b128 v[190:193], v200 offset:36864
	ds_read_b128 v[194:197], v200 offset:37888
	ds_read_b128 v[202:205], v200 offset:38912
	ds_read_b128 v[206:209], v200 offset:39936
	global_load_lds_dwordx4 v[218:219], off
	v_lshl_add_u64 v[218:219], s[20:21], 0, v[178:179]
	s_mov_b32 m0, s46
	s_nop 0
	global_load_lds_dwordx4 v[218:219], off
	s_waitcnt vmcnt(8)
	s_waitcnt lgkmcnt(0)
	s_barrier
	s_setprio 1
	s_waitcnt lgkmcnt(0)
	v_mfma_f32_16x16x32_bf16 v[144:147], v[124:127], v[164:167], v[144:147]
	v_mfma_f32_16x16x32_bf16 v[140:143], v[132:135], v[164:167], v[140:143]
	v_mfma_f32_16x16x32_bf16 v[108:111], v[132:135], v[172:175], v[108:111]
	v_mfma_f32_16x16x32_bf16 v[112:115], v[124:127], v[172:175], v[112:115]
	v_mfma_f32_16x16x32_bf16 v[100:103], v[124:127], v[190:193], v[100:103]
	v_mfma_f32_16x16x32_bf16 v[92:95], v[132:135], v[190:193], v[92:95]
	v_mfma_f32_16x16x32_bf16 v[76:79], v[132:135], v[202:205], v[76:79]
	v_mfma_f32_16x16x32_bf16 v[84:87], v[124:127], v[202:205], v[84:87]
	v_mfma_f32_16x16x32_bf16 v[144:147], v[128:131], v[168:171], v[144:147]
	v_mfma_f32_16x16x32_bf16 v[140:143], v[136:139], v[168:171], v[140:143]
	v_mfma_f32_16x16x32_bf16 v[108:111], v[136:139], v[186:189], v[108:111]
	v_mfma_f32_16x16x32_bf16 v[112:115], v[128:131], v[186:189], v[112:115]
	v_mfma_f32_16x16x32_bf16 v[100:103], v[128:131], v[194:197], v[100:103]
	v_mfma_f32_16x16x32_bf16 v[92:95], v[136:139], v[194:197], v[92:95]
	v_mfma_f32_16x16x32_bf16 v[76:79], v[136:139], v[206:209], v[76:79]
	v_mfma_f32_16x16x32_bf16 v[84:87], v[128:131], v[206:209], v[84:87]
	s_setprio 0
	s_setprio 1
	v_mfma_f32_16x16x32_bf16 v[120:123], v[148:151], v[164:167], v[120:123]
	v_mfma_f32_16x16x32_bf16 v[116:119], v[156:159], v[164:167], v[116:119]
	v_mfma_f32_16x16x32_bf16 v[96:99], v[156:159], v[172:175], v[96:99]
	v_mfma_f32_16x16x32_bf16 v[104:107], v[148:151], v[172:175], v[104:107]
	v_mfma_f32_16x16x32_bf16 v[88:91], v[148:151], v[190:193], v[88:91]
	v_mfma_f32_16x16x32_bf16 v[80:83], v[156:159], v[190:193], v[80:83]
	v_mfma_f32_16x16x32_bf16 v[68:71], v[156:159], v[202:205], v[68:71]
	v_mfma_f32_16x16x32_bf16 v[72:75], v[148:151], v[202:205], v[72:75]
	v_mfma_f32_16x16x32_bf16 v[120:123], v[152:155], v[168:171], v[120:123]
	v_mfma_f32_16x16x32_bf16 v[116:119], v[160:163], v[168:171], v[116:119]
	v_mfma_f32_16x16x32_bf16 v[96:99], v[160:163], v[186:189], v[96:99]
	v_mfma_f32_16x16x32_bf16 v[104:107], v[152:155], v[186:189], v[104:107]
	v_mfma_f32_16x16x32_bf16 v[88:91], v[152:155], v[194:197], v[88:91]
	v_mfma_f32_16x16x32_bf16 v[80:83], v[160:163], v[194:197], v[80:83]
	v_mfma_f32_16x16x32_bf16 v[68:71], v[160:163], v[206:209], v[68:71]
	v_mfma_f32_16x16x32_bf16 v[72:75], v[152:155], v[206:209], v[72:75]
	s_setprio 0
	s_barrier
; #define PG8_BAR __builtin_amdgcn_s_barrier()
;     __device__ __forceinline__ void operator()(const f32x4 (&acc)[2][2][4][2], const Unit& u, int wr, int wc, int fr, int fq) const {
;         const int row0 = u.pm * BM + wr * 64 + fr; const int col0 = u.pn * BM + wc * 32 + 8 * fq;
;         const float* gp = gate + (size_t)((u.pm * BM) >> 12) * gstride + col0;
;         f32x4 gv[2][2];
; #pragma unroll
;         for (int bj = 0; bj < 2; ++bj)
; #pragma unroll
;             for (int n = 0; n < 2; ++n) gv[bj][n] = *(const f32x4*)(gp + bj * HALF + n * 4);
;         if (base_f32) { const float* bp = (const float*)base;
; #pragma unroll
;             for (int ai = 0; ai < 2; ++ai)
; #pragma unroll
;                 for (int m2 = 0; m2 < 2; ++m2) { f32x4 bs[2][2][2];
; #pragma unroll
;                     for (int mm = 0; mm < 2; ++mm) { const size_t off = (size_t)(row0 + ai * HALF + (2 * m2 + mm) * 16) * ldc + col0;
; #pragma unroll
;                         for (int bj = 0; bj < 2; ++bj)
; #pragma unroll
;                             for (int n = 0; n < 2; ++n) bs[mm][bj][n] = *(const f32x4*)(bp + off + bj * HALF + n * 4); }
; #pragma unroll
;                     for (int mm = 0; mm < 2; ++mm) { const size_t off = (size_t)(row0 + ai * HALF + (2 * m2 + mm) * 16) * ldc + col0;
; #pragma unroll
;                         for (int bj = 0; bj < 2; ++bj) { const f32x4 v0 = bs[mm][bj][0] + gv[bj][0] * acc[ai][bj][2 * m2 + mm][0], v1 = bs[mm][bj][1] + gv[bj][1] * acc[ai][bj][2 * m2 + mm][1];
;                             u32x4 w; w.x = cvt_pk_bf16(v0[0], v0[1]); w.y = cvt_pk_bf16(v0[2], v0[3]); w.z = cvt_pk_bf16(v1[0], v1[1]); w.w = cvt_pk_bf16(v1[2], v1[3]);
; template <class Epi, class Sched, bool ALIGN_EPI = false, bool SP2 = false>
; __device__ __forceinline__ void gemm_phase(PG8_LAS unsigned char* lds, const Gemm g, const Sched& S, const Epi& E) {
;     ...
;             PG8_LDB(B0, 1, 0); PG8_LDB(B1, 1, 1); PG8_SCHED; PG8_LDA(At, 1, 0); PG8_STAGE(PG8_SA(0, 1), a2 + hstep, voffA);
;             PG8_WAIT_V(8); PG8_WAIT_L(0); PG8_BAR; PG8_MMA(0, 0, At, B0); PG8_MMA(0, 1, At, B1); PG8_BAR; PG8_SCHED;
;             PG8_LDA(At, 1, 1); PG8_STAGE(PG8_SB(1, 0), b3, voffB); PG8_STAGE(PG8_SB(1, 1), b3 + hstep, voffB); PG8_STAGE(PG8_SA(1, 0), a3, voffA);
;             PG8_WAIT_V(8); PG8_WAIT_L(0); PG8_BAR; PG8_MMA(1, 0, At, B0); PG8_MMA(1, 1, At, B1); PG8_BAR; PG8_SCHED;
	s_add_i32 s20, s30, s13
	v_lshl_add_u64 v[210:211], v[210:211], 0, s[28:29]
	s_mov_b32 m0, s20
	ds_read_b128 v[164:167], v200 offset:49152
	ds_read_b128 v[168:171], v200 offset:50176
	ds_read_b128 v[172:175], v200 offset:51200
	ds_read_b128 v[186:189], v200 offset:52224
	ds_read_b128 v[190:193], v200 offset:53248
	ds_read_b128 v[194:197], v200 offset:54272
	ds_read_b128 v[202:205], v200 offset:55296
	ds_read_b128 v[206:209], v200 offset:56320
	global_load_lds_dwordx4 v[210:211], off
	s_add_i32 m0, s20, 0x2000
	s_add_u32 s20, s26, 0x160080
	v_lshl_add_u64 v[210:211], v[212:213], 0, s[28:29]
	s_addc_u32 s21, s27, 0
	s_add_i32 s26, s31, s13
	global_load_lds_dwordx4 v[210:211], off
	v_lshl_add_u64 v[210:211], s[20:21], 0, v[2:3]
	s_mov_b32 m0, s26
	s_nop 0
	global_load_lds_dwordx4 v[210:211], off
	v_lshl_add_u64 v[210:211], s[20:21], 0, v[180:181]
	s_add_i32 m0, s26, 0x2000
	s_nop 0
	global_load_lds_dwordx4 v[210:211], off
	v_lshl_add_u64 v[210:211], v[214:215], 0, s[28:29]
	s_mov_b32 m0, s49
	s_nop 0
	global_load_lds_dwordx4 v[210:211], off
	v_lshl_add_u64 v[210:211], v[216:217], 0, s[28:29]
	s_mov_b32 m0, s50
	s_nop 0
	global_load_lds_dwordx4 v[210:211], off
	s_waitcnt vmcnt(8)
	s_waitcnt lgkmcnt(0)
	s_barrier
	s_setprio 1
	s_waitcnt lgkmcnt(0)
	v_mfma_f32_16x16x32_bf16 v[64:67], v[124:127], v[164:167], v[64:67]
	v_mfma_f32_16x16x32_bf16 v[60:63], v[132:135], v[164:167], v[60:63]
	v_mfma_f32_16x16x32_bf16 v[44:47], v[132:135], v[172:175], v[44:47]
	v_mfma_f32_16x16x32_bf16 v[52:55], v[124:127], v[172:175], v[52:55]
	v_mfma_f32_16x16x32_bf16 v[36:39], v[124:127], v[190:193], v[36:39]
	v_mfma_f32_16x16x32_bf16 v[28:31], v[132:135], v[190:193], v[28:31]
	v_mfma_f32_16x16x32_bf16 v[12:15], v[132:135], v[202:205], v[12:15]
	v_mfma_f32_16x16x32_bf16 v[20:23], v[124:127], v[202:205], v[20:23]
	v_mfma_f32_16x16x32_bf16 v[64:67], v[128:131], v[168:171], v[64:67]
	v_mfma_f32_16x16x32_bf16 v[60:63], v[136:139], v[168:171], v[60:63]
	v_mfma_f32_16x16x32_bf16 v[44:47], v[136:139], v[186:189], v[44:47]
	v_mfma_f32_16x16x32_bf16 v[52:55], v[128:131], v[186:189], v[52:55]
	v_mfma_f32_16x16x32_bf16 v[36:39], v[128:131], v[194:197], v[36:39]
	v_mfma_f32_16x16x32_bf16 v[28:31], v[136:139], v[194:197], v[28:31]
	v_mfma_f32_16x16x32_bf16 v[12:15], v[136:139], v[206:209], v[12:15]
	v_mfma_f32_16x16x32_bf16 v[20:23], v[128:131], v[206:209], v[20:23]
	s_setprio 0
	s_setprio 1
	v_mfma_f32_16x16x32_bf16 v[56:59], v[148:151], v[164:167], v[56:59]
	v_mfma_f32_16x16x32_bf16 v[48:51], v[156:159], v[164:167], v[48:51]
	v_mfma_f32_16x16x32_bf16 v[32:35], v[156:159], v[172:175], v[32:35]
	v_mfma_f32_16x16x32_bf16 v[40:43], v[148:151], v[172:175], v[40:43]
	v_mfma_f32_16x16x32_bf16 v[24:27], v[148:151], v[190:193], v[24:27]
	v_mfma_f32_16x16x32_bf16 v[16:19], v[156:159], v[190:193], v[16:19]
	v_mfma_f32_16x16x32_bf16 v[4:7], v[156:159], v[202:205], v[4:7]
	v_mfma_f32_16x16x32_bf16 v[8:11], v[148:151], v[202:205], v[8:11]
	v_mfma_f32_16x16x32_bf16 v[56:59], v[152:155], v[168:171], v[56:59]
	v_mfma_f32_16x16x32_bf16 v[48:51], v[160:163], v[168:171], v[48:51]
	v_mfma_f32_16x16x32_bf16 v[32:35], v[160:163], v[186:189], v[32:35]
	v_mfma_f32_16x16x32_bf16 v[40:43], v[152:155], v[186:189], v[40:43]
	v_mfma_f32_16x16x32_bf16 v[24:27], v[152:155], v[194:197], v[24:27]
	v_mfma_f32_16x16x32_bf16 v[16:19], v[160:163], v[194:197], v[16:19]
	v_mfma_f32_16x16x32_bf16 v[4:7], v[160:163], v[206:209], v[4:7]
	v_mfma_f32_16x16x32_bf16 v[8:11], v[152:155], v[206:209], v[8:11]
	s_setprio 0
	s_barrier
	s_add_i32 s42, s42, 2
	s_add_u32 s40, s40, 0x100
	s_addc_u32 s41, s41, 0
	s_cmpk_gt_u32 s42, 0x55
	s_mov_b64 s[20:21], s[24:25]
	s_cbranch_scc0 .LBB0_2238
	v_lshl_or_b32 v148, s54, 8, v199
	s_ashr_i32 s20, s33, 4
	s_mul_hi_i32 s21, s20, 0xc000
	s_mul_i32 s20, s20, 0xc000
	v_ashrrev_i32_e32 v149, 31, v148
	v_lshl_add_u32 v150, s33, 8, v1
	s_add_u32 s20, s47, s20
	v_ashrrev_i32_e32 v151, 31, v150
	v_lshlrev_b64 v[186:187], 1, v[148:149]
	s_addc_u32 s21, s48, s21
	v_lshl_add_u64 v[188:189], s[14:15], 0, v[186:187]
	v_lshlrev_b64 v[190:191], 12, v[150:151]
	v_lshl_add_u64 v[124:125], v[148:149], 2, s[20:21]
	v_lshl_add_u64 v[148:149], v[188:189], 0, v[190:191]
	flat_load_dwordx4 v[136:139], v[124:125]
	flat_load_dwordx4 v[132:135], v[124:125] offset:16
	flat_load_dwordx4 v[128:131], v[124:125] offset:512
	s_nop 0
	flat_load_dwordx4 v[124:127], v[124:125] offset:528
	s_nop 0
	flat_load_dwordx4 v[202:205], v[148:149]
	flat_load_dwordx4 v[172:175], v[148:149] offset:256
	v_or_b32_e32 v148, 16, v150
	v_ashrrev_i32_e32 v149, 31, v148
	v_lshlrev_b64 v[196:197], 12, v[148:149]
	v_lshl_add_u64 v[148:149], v[188:189], 0, v[196:197]
	flat_load_dwordx4 v[168:171], v[148:149]
	flat_load_dwordx4 v[164:167], v[148:149] offset:256
	v_or_b32_e32 v148, 32, v150
	v_ashrrev_i32_e32 v149, 31, v148
	v_lshlrev_b64 v[194:195], 12, v[148:149]
	v_lshl_add_u64 v[148:149], v[188:189], 0, v[194:195]
	flat_load_dwordx4 v[160:163], v[148:149]
	flat_load_dwordx4 v[152:155], v[148:149] offset:256
	v_or_b32_e32 v148, 48, v150
	v_ashrrev_i32_e32 v149, 31, v148
	v_lshlrev_b64 v[192:193], 12, v[148:149]
	v_lshl_add_u64 v[148:149], v[188:189], 0, v[192:193]
	flat_load_dwordx4 v[156:159], v[148:149]
	s_nop 0
	flat_load_dwordx4 v[148:151], v[148:149] offset:256
	s_mov_b64 s[20:21], 0x80000
	s_and_b64 vcc, exec, s[38:39]
	s_mov_b32 s54, s52
	s_mov_b32 s33, s53
	s_mov_b64 s[24:25], s[22:23]
	s_waitcnt vmcnt(0) lgkmcnt(0)
; __device__ __forceinline__ unsigned cvt_pk_bf16(float lo, float hi) { unsigned r; asm volatile("v_cvt_pk_bf16_f32 %0, %1, %2" : "=v"(r) : "v"(lo), "v"(hi)); return r; }
;     __device__ __forceinline__ void operator()(const f32x4 (&acc)[2][2][4][2], const Unit& u, int wr, int wc, int fr, int fq) const {
;     ...
;                 for (int m = 0; m < 4; ++m) { const size_t off = (size_t)(row0 + ai * HALF + m * 16) * ldc + col0;
; #pragma unroll
;                     for (int bj = 0; bj < 2; ++bj) { const u32x4 r = bs[m][bj]; const f32x4 a0 = acc[ai][bj][m][0], a1 = acc[ai][bj][m][1];
;                         u32x4 w;
;                         w.x = cvt_pk_bf16(__builtin_bit_cast(float, r.x << 16) + gv[bj][0][0] * a0[0], __builtin_bit_cast(float, r.x & 0xffff0000u) + gv[bj][0][1] * a0[1]);
;                         w.y = cvt_pk_bf16(__builtin_bit_cast(float, r.y << 16) + gv[bj][0][2] * a0[2], __builtin_bit_cast(float, r.y & 0xffff0000u) + gv[bj][0][3] * a0[3]);
;                         w.z = cvt_pk_bf16(__builtin_bit_cast(float, r.z << 16) + gv[bj][1][0] * a1[0], __builtin_bit_cast(float, r.z & 0xffff0000u) + gv[bj][1][1] * a1[1]);
;                         w.w = cvt_pk_bf16(__builtin_bit_cast(float, r.w << 16) + gv[bj][1][2] * a1[2], __builtin_bit_cast(float, r.w & 0xffff0000u) + gv[bj][1][3] * a1[3]);
;                         *(u32x4*)(out + off + bj * HALF) = w; } }
	v_lshlrev_b32_e32 v201, 16, v202
	v_fmac_f32_e32 v201, v144, v136
	v_and_b32_e32 v144, 0xffff0000, v202
	v_fmac_f32_e32 v144, v145, v137
	v_lshlrev_b32_e32 v145, 16, v203
	v_fmac_f32_e32 v145, v146, v138
	v_and_b32_e32 v146, 0xffff0000, v203
	v_fmac_f32_e32 v146, v147, v139
	v_cvt_pk_bf16_f32 v144, v201, v144
	v_cvt_pk_bf16_f32 v145, v145, v146
	v_lshlrev_b32_e32 v146, 16, v204
	v_fmac_f32_e32 v146, v140, v132
	v_and_b32_e32 v140, 0xffff0000, v204
	v_fmac_f32_e32 v140, v141, v133
	v_cvt_pk_bf16_f32 v146, v146, v140
	v_lshlrev_b32_e32 v140, 16, v205
	v_fmac_f32_e32 v140, v142, v134
	v_lshlrev_b32_e32 v142, 16, v172
	v_and_b32_e32 v141, 0xffff0000, v205
	v_fmac_f32_e32 v142, v120, v128
	v_and_b32_e32 v120, 0xffff0000, v172
	v_fmac_f32_e32 v141, v143, v135
	v_fmac_f32_e32 v120, v121, v129
	v_lshlrev_b32_e32 v121, 16, v173
	v_cvt_pk_bf16_f32 v147, v140, v141
	v_lshl_add_u64 v[140:141], s[14:15], 0, v[190:191]
	v_fmac_f32_e32 v121, v122, v130
	v_and_b32_e32 v122, 0xffff0000, v173
	v_lshl_add_u64 v[140:141], v[140:141], 0, v[186:187]
	v_fmac_f32_e32 v122, v123, v131
	flat_store_dwordx4 v[140:141], v[144:147]
	v_cvt_pk_bf16_f32 v120, v142, v120
	v_cvt_pk_bf16_f32 v121, v121, v122
	v_lshlrev_b32_e32 v122, 16, v174
	v_fmac_f32_e32 v122, v116, v124
	v_and_b32_e32 v116, 0xffff0000, v174
	v_fmac_f32_e32 v116, v117, v125
	v_cvt_pk_bf16_f32 v122, v122, v116
	v_lshlrev_b32_e32 v116, 16, v175
	v_fmac_f32_e32 v116, v118, v126
	v_and_b32_e32 v117, 0xffff0000, v175
	v_fmac_f32_e32 v117, v119, v127
	v_cvt_pk_bf16_f32 v123, v116, v117
	v_lshlrev_b32_e32 v116, 16, v168
	v_fmac_f32_e32 v116, v112, v136
	v_and_b32_e32 v112, 0xffff0000, v168
	v_fmac_f32_e32 v112, v113, v137
	v_lshlrev_b32_e32 v113, 16, v169
	v_fmac_f32_e32 v113, v114, v138
	v_and_b32_e32 v114, 0xffff0000, v169
	v_fmac_f32_e32 v114, v115, v139
	flat_store_dwordx4 v[140:141], v[120:123] offset:256
	v_cvt_pk_bf16_f32 v112, v116, v112
	v_cvt_pk_bf16_f32 v113, v113, v114
	v_lshlrev_b32_e32 v114, 16, v170
	v_fmac_f32_e32 v114, v108, v132
	v_and_b32_e32 v108, 0xffff0000, v170
	v_fmac_f32_e32 v108, v109, v133
	v_cvt_pk_bf16_f32 v114, v114, v108
	v_lshlrev_b32_e32 v108, 16, v171
	v_fmac_f32_e32 v108, v110, v134
	v_lshlrev_b32_e32 v110, 16, v164
	v_and_b32_e32 v109, 0xffff0000, v171
	v_fmac_f32_e32 v110, v104, v128
	v_and_b32_e32 v104, 0xffff0000, v164
	v_fmac_f32_e32 v109, v111, v135
	v_fmac_f32_e32 v104, v105, v129
	v_lshlrev_b32_e32 v105, 16, v165
	v_cvt_pk_bf16_f32 v115, v108, v109
	v_lshl_add_u64 v[108:109], s[14:15], 0, v[196:197]
	v_fmac_f32_e32 v105, v106, v130
	v_and_b32_e32 v106, 0xffff0000, v165
	v_lshl_add_u64 v[108:109], v[108:109], 0, v[186:187]
	v_fmac_f32_e32 v106, v107, v131
	flat_store_dwordx4 v[108:109], v[112:115]
	v_cvt_pk_bf16_f32 v104, v110, v104
	v_cvt_pk_bf16_f32 v105, v105, v106
	v_lshlrev_b32_e32 v106, 16, v166
	v_fmac_f32_e32 v106, v96, v124
	v_and_b32_e32 v96, 0xffff0000, v166
	v_fmac_f32_e32 v96, v97, v125
	v_cvt_pk_bf16_f32 v106, v106, v96
	v_lshlrev_b32_e32 v96, 16, v167
	v_and_b32_e32 v97, 0xffff0000, v167
	v_fmac_f32_e32 v96, v98, v126
	v_fmac_f32_e32 v97, v99, v127
	v_cvt_pk_bf16_f32 v107, v96, v97
	v_lshlrev_b32_e32 v96, 16, v160
	v_and_b32_e32 v97, 0xffff0000, v160
	v_fmac_f32_e32 v96, v100, v136
	v_fmac_f32_e32 v97, v101, v137
	flat_store_dwordx4 v[108:109], v[104:107] offset:256
	v_cvt_pk_bf16_f32 v96, v96, v97
	v_lshlrev_b32_e32 v97, 16, v161
	v_and_b32_e32 v98, 0xffff0000, v161
	v_fmac_f32_e32 v97, v102, v138
	v_fmac_f32_e32 v98, v103, v139
	v_cvt_pk_bf16_f32 v97, v97, v98
	v_lshlrev_b32_e32 v98, 16, v162
	v_fmac_f32_e32 v98, v92, v132
	v_and_b32_e32 v92, 0xffff0000, v162
	v_fmac_f32_e32 v92, v93, v133
	v_cvt_pk_bf16_f32 v98, v98, v92
	v_lshlrev_b32_e32 v92, 16, v163
	v_fmac_f32_e32 v92, v94, v134
	v_lshlrev_b32_e32 v94, 16, v152
	v_and_b32_e32 v93, 0xffff0000, v163
	v_fmac_f32_e32 v94, v88, v128
	v_and_b32_e32 v88, 0xffff0000, v152
	v_fmac_f32_e32 v93, v95, v135
	v_fmac_f32_e32 v88, v89, v129
	v_lshlrev_b32_e32 v89, 16, v153
	v_cvt_pk_bf16_f32 v99, v92, v93
	v_lshl_add_u64 v[92:93], s[14:15], 0, v[194:195]
	v_fmac_f32_e32 v89, v90, v130
	v_and_b32_e32 v90, 0xffff0000, v153
	v_lshl_add_u64 v[92:93], v[92:93], 0, v[186:187]
	v_fmac_f32_e32 v90, v91, v131
	flat_store_dwordx4 v[92:93], v[96:99]
	v_cvt_pk_bf16_f32 v88, v94, v88
	v_cvt_pk_bf16_f32 v89, v89, v90
	v_lshlrev_b32_e32 v90, 16, v154
	v_fmac_f32_e32 v90, v80, v124
	v_and_b32_e32 v80, 0xffff0000, v154
	v_fmac_f32_e32 v80, v81, v125
	v_cvt_pk_bf16_f32 v90, v90, v80
	v_lshlrev_b32_e32 v80, 16, v155
	v_and_b32_e32 v81, 0xffff0000, v155
	v_fmac_f32_e32 v80, v82, v126
	v_fmac_f32_e32 v81, v83, v127
	v_cvt_pk_bf16_f32 v91, v80, v81
	v_lshlrev_b32_e32 v80, 16, v156
	v_and_b32_e32 v81, 0xffff0000, v156
	v_fmac_f32_e32 v80, v84, v136
	v_fmac_f32_e32 v81, v85, v137
	flat_store_dwordx4 v[92:93], v[88:91] offset:256
	v_cvt_pk_bf16_f32 v80, v80, v81
	v_lshlrev_b32_e32 v81, 16, v157
	v_and_b32_e32 v82, 0xffff0000, v157
	v_fmac_f32_e32 v81, v86, v138
	v_fmac_f32_e32 v82, v87, v139
	v_cvt_pk_bf16_f32 v81, v81, v82
	v_lshlrev_b32_e32 v82, 16, v158
	v_fmac_f32_e32 v82, v76, v132
	v_and_b32_e32 v76, 0xffff0000, v158
	v_fmac_f32_e32 v76, v77, v133
	v_cvt_pk_bf16_f32 v82, v82, v76
	v_lshlrev_b32_e32 v76, 16, v159
	v_fmac_f32_e32 v76, v78, v134
	v_lshlrev_b32_e32 v78, 16, v148
	v_and_b32_e32 v77, 0xffff0000, v159
	v_fmac_f32_e32 v78, v72, v128
	v_and_b32_e32 v72, 0xffff0000, v148
	v_fmac_f32_e32 v77, v79, v135
	v_fmac_f32_e32 v72, v73, v129
	v_lshlrev_b32_e32 v73, 16, v149
	v_cvt_pk_bf16_f32 v83, v76, v77
	v_lshl_add_u64 v[76:77], s[14:15], 0, v[192:193]
	v_fmac_f32_e32 v73, v74, v130
	v_and_b32_e32 v74, 0xffff0000, v149
; __device__ __forceinline__ unsigned cvt_pk_bf16(float lo, float hi) { unsigned r; asm volatile("v_cvt_pk_bf16_f32 %0, %1, %2" : "=v"(r) : "v"(lo), "v"(hi)); return r; }
;     __device__ __forceinline__ void operator()(const f32x4 (&acc)[2][2][4][2], const Unit& u, int wr, int wc, int fr, int fq) const {
;     ...
;             for (int ai = 0; ai < 2; ++ai) { u32x4 bs[4][2];
; #pragma unroll
;                 for (int m = 0; m < 4; ++m) { const size_t off = (size_t)(row0 + ai * HALF + m * 16) * ldc + col0;
; #pragma unroll
;                     for (int bj = 0; bj < 2; ++bj) bs[m][bj] = *(const u32x4*)(bp + off + bj * HALF); }
; #pragma unroll
;                 for (int m = 0; m < 4; ++m) { const size_t off = (size_t)(row0 + ai * HALF + m * 16) * ldc + col0;
; #pragma unroll
;                     for (int bj = 0; bj < 2; ++bj) { const u32x4 r = bs[m][bj]; const f32x4 a0 = acc[ai][bj][m][0], a1 = acc[ai][bj][m][1];
;                         u32x4 w;
;                         w.x = cvt_pk_bf16(__builtin_bit_cast(float, r.x << 16) + gv[bj][0][0] * a0[0], __builtin_bit_cast(float, r.x & 0xffff0000u) + gv[bj][0][1] * a0[1]);
;                         w.y = cvt_pk_bf16(__builtin_bit_cast(float, r.y << 16) + gv[bj][0][2] * a0[2], __builtin_bit_cast(float, r.y & 0xffff0000u) + gv[bj][0][3] * a0[3]);
;                         w.z = cvt_pk_bf16(__builtin_bit_cast(float, r.z << 16) + gv[bj][1][0] * a1[0], __builtin_bit_cast(float, r.z & 0xffff0000u) + gv[bj][1][1] * a1[1]);
;                         w.w = cvt_pk_bf16(__builtin_bit_cast(float, r.w << 16) + gv[bj][1][2] * a1[2], __builtin_bit_cast(float, r.w & 0xffff0000u) + gv[bj][1][3] * a1[3]);
;                         *(u32x4*)(out + off + bj * HALF) = w; } }
	v_lshl_add_u64 v[76:77], v[76:77], 0, v[186:187]
	v_fmac_f32_e32 v74, v75, v131
	flat_store_dwordx4 v[76:77], v[80:83]
	v_cvt_pk_bf16_f32 v72, v78, v72
	v_cvt_pk_bf16_f32 v73, v73, v74
	v_lshlrev_b32_e32 v74, 16, v150
	v_fmac_f32_e32 v74, v68, v124
	v_and_b32_e32 v68, 0xffff0000, v150
	v_fmac_f32_e32 v68, v69, v125
	v_cvt_pk_bf16_f32 v74, v74, v68
	v_lshlrev_b32_e32 v68, 16, v151
	v_and_b32_e32 v69, 0xffff0000, v151
	v_fmac_f32_e32 v68, v70, v126
	v_fmac_f32_e32 v69, v71, v127
	v_cvt_pk_bf16_f32 v75, v68, v69
	flat_store_dwordx4 v[76:77], v[72:75] offset:256
	v_lshl_add_u64 v[100:101], v[190:191], 0, s[20:21]
	v_lshl_add_u64 v[68:69], v[188:189], 0, v[100:101]
	flat_load_dwordx4 v[72:75], v[68:69]
	flat_load_dwordx4 v[76:79], v[68:69] offset:256
	s_mov_b64 s[20:21], 0x90000
	v_lshl_add_u64 v[102:103], v[190:191], 0, s[20:21]
	v_lshl_add_u64 v[68:69], v[188:189], 0, v[102:103]
	flat_load_dwordx4 v[80:83], v[68:69]
	flat_load_dwordx4 v[84:87], v[68:69] offset:256
	s_mov_b64 s[20:21], 0xa0000
	v_lshl_add_u64 v[104:105], v[190:191], 0, s[20:21]
	v_lshl_add_u64 v[68:69], v[188:189], 0, v[104:105]
	flat_load_dwordx4 v[88:91], v[68:69]
	flat_load_dwordx4 v[92:95], v[68:69] offset:256
	s_mov_b64 s[20:21], 0xb0000
	v_lshl_add_u64 v[106:107], v[190:191], 0, s[20:21]
	v_lshl_add_u64 v[68:69], v[188:189], 0, v[106:107]
	flat_load_dwordx4 v[96:99], v[68:69]
	s_nop 0
	flat_load_dwordx4 v[68:71], v[68:69] offset:256
	s_mov_b64 s[20:21], s[16:17]
	s_waitcnt vmcnt(0) lgkmcnt(0)
; __device__ __forceinline__ unsigned cvt_pk_bf16(float lo, float hi) { unsigned r; asm volatile("v_cvt_pk_bf16_f32 %0, %1, %2" : "=v"(r) : "v"(lo), "v"(hi)); return r; }
;     __device__ __forceinline__ void operator()(const f32x4 (&acc)[2][2][4][2], const Unit& u, int wr, int wc, int fr, int fq) const {
;     ...
;                 for (int m = 0; m < 4; ++m) { const size_t off = (size_t)(row0 + ai * HALF + m * 16) * ldc + col0;
; #pragma unroll
;                     for (int bj = 0; bj < 2; ++bj) { const u32x4 r = bs[m][bj]; const f32x4 a0 = acc[ai][bj][m][0], a1 = acc[ai][bj][m][1];
;                         u32x4 w;
;                         w.x = cvt_pk_bf16(__builtin_bit_cast(float, r.x << 16) + gv[bj][0][0] * a0[0], __builtin_bit_cast(float, r.x & 0xffff0000u) + gv[bj][0][1] * a0[1]);
;                         w.y = cvt_pk_bf16(__builtin_bit_cast(float, r.y << 16) + gv[bj][0][2] * a0[2], __builtin_bit_cast(float, r.y & 0xffff0000u) + gv[bj][0][3] * a0[3]);
;                         w.z = cvt_pk_bf16(__builtin_bit_cast(float, r.z << 16) + gv[bj][1][0] * a1[0], __builtin_bit_cast(float, r.z & 0xffff0000u) + gv[bj][1][1] * a1[1]);
;                         w.w = cvt_pk_bf16(__builtin_bit_cast(float, r.w << 16) + gv[bj][1][2] * a1[2], __builtin_bit_cast(float, r.w & 0xffff0000u) + gv[bj][1][3] * a1[3]);
;                         *(u32x4*)(out + off + bj * HALF) = w; } }
;                 asm volatile("" ::: "memory"); }
	v_lshlrev_b32_e32 v108, 16, v72
	v_fmac_f32_e32 v108, v64, v136
	v_and_b32_e32 v64, 0xffff0000, v72
	v_fmac_f32_e32 v64, v65, v137
	v_lshlrev_b32_e32 v65, 16, v73
	v_fmac_f32_e32 v65, v66, v138
	v_and_b32_e32 v66, 0xffff0000, v73
	v_fmac_f32_e32 v66, v67, v139
	v_cvt_pk_bf16_f32 v64, v108, v64
	v_cvt_pk_bf16_f32 v65, v65, v66
	v_lshlrev_b32_e32 v66, 16, v74
	v_fmac_f32_e32 v66, v60, v132
	v_and_b32_e32 v60, 0xffff0000, v74
	v_fmac_f32_e32 v60, v61, v133
	v_cvt_pk_bf16_f32 v66, v66, v60
	v_lshlrev_b32_e32 v60, 16, v75
	v_fmac_f32_e32 v60, v62, v134
	v_lshlrev_b32_e32 v62, 16, v76
	v_and_b32_e32 v61, 0xffff0000, v75
	v_fmac_f32_e32 v62, v56, v128
	v_and_b32_e32 v56, 0xffff0000, v76
	v_fmac_f32_e32 v61, v63, v135
	v_fmac_f32_e32 v56, v57, v129
	v_lshlrev_b32_e32 v57, 16, v77
	v_cvt_pk_bf16_f32 v67, v60, v61
	v_lshl_add_u64 v[60:61], s[14:15], 0, v[100:101]
	v_fmac_f32_e32 v57, v58, v130
	v_and_b32_e32 v58, 0xffff0000, v77
	v_lshl_add_u64 v[60:61], v[60:61], 0, v[186:187]
	v_fmac_f32_e32 v58, v59, v131
	flat_store_dwordx4 v[60:61], v[64:67]
	v_cvt_pk_bf16_f32 v56, v62, v56
	v_cvt_pk_bf16_f32 v57, v57, v58
	v_lshlrev_b32_e32 v58, 16, v78
	v_fmac_f32_e32 v58, v48, v124
	v_and_b32_e32 v48, 0xffff0000, v78
	v_fmac_f32_e32 v48, v49, v125
	v_cvt_pk_bf16_f32 v58, v58, v48
	v_lshlrev_b32_e32 v48, 16, v79
	v_and_b32_e32 v49, 0xffff0000, v79
	v_fmac_f32_e32 v48, v50, v126
	v_fmac_f32_e32 v49, v51, v127
	v_cvt_pk_bf16_f32 v59, v48, v49
	v_lshlrev_b32_e32 v48, 16, v80
	v_and_b32_e32 v49, 0xffff0000, v80
	v_fmac_f32_e32 v48, v52, v136
	v_fmac_f32_e32 v49, v53, v137
	flat_store_dwordx4 v[60:61], v[56:59] offset:256
	v_cvt_pk_bf16_f32 v48, v48, v49
	v_lshlrev_b32_e32 v49, 16, v81
	v_and_b32_e32 v50, 0xffff0000, v81
	v_fmac_f32_e32 v49, v54, v138
	v_fmac_f32_e32 v50, v55, v139
	v_cvt_pk_bf16_f32 v49, v49, v50
	v_lshlrev_b32_e32 v50, 16, v82
	v_fmac_f32_e32 v50, v44, v132
	v_and_b32_e32 v44, 0xffff0000, v82
	v_fmac_f32_e32 v44, v45, v133
	v_cvt_pk_bf16_f32 v50, v50, v44
	v_lshlrev_b32_e32 v44, 16, v83
	v_fmac_f32_e32 v44, v46, v134
	v_lshlrev_b32_e32 v46, 16, v84
	v_and_b32_e32 v45, 0xffff0000, v83
	v_fmac_f32_e32 v46, v40, v128
	v_and_b32_e32 v40, 0xffff0000, v84
	v_fmac_f32_e32 v45, v47, v135
	v_fmac_f32_e32 v40, v41, v129
	v_lshlrev_b32_e32 v41, 16, v85
	v_cvt_pk_bf16_f32 v51, v44, v45
	v_lshl_add_u64 v[44:45], s[14:15], 0, v[102:103]
	v_fmac_f32_e32 v41, v42, v130
	v_and_b32_e32 v42, 0xffff0000, v85
	v_lshl_add_u64 v[44:45], v[44:45], 0, v[186:187]
	v_fmac_f32_e32 v42, v43, v131
	flat_store_dwordx4 v[44:45], v[48:51]
	v_cvt_pk_bf16_f32 v40, v46, v40
	v_cvt_pk_bf16_f32 v41, v41, v42
	v_lshlrev_b32_e32 v42, 16, v86
	v_fmac_f32_e32 v42, v32, v124
	v_and_b32_e32 v32, 0xffff0000, v86
	v_fmac_f32_e32 v32, v33, v125
	v_cvt_pk_bf16_f32 v42, v42, v32
	v_lshlrev_b32_e32 v32, 16, v87
	v_and_b32_e32 v33, 0xffff0000, v87
	v_fmac_f32_e32 v32, v34, v126
	v_fmac_f32_e32 v33, v35, v127
	v_cvt_pk_bf16_f32 v43, v32, v33
	v_lshlrev_b32_e32 v32, 16, v88
	v_and_b32_e32 v33, 0xffff0000, v88
	v_fmac_f32_e32 v32, v36, v136
	v_fmac_f32_e32 v33, v37, v137
	flat_store_dwordx4 v[44:45], v[40:43] offset:256
	v_cvt_pk_bf16_f32 v32, v32, v33
	v_lshlrev_b32_e32 v33, 16, v89
	v_and_b32_e32 v34, 0xffff0000, v89
	v_fmac_f32_e32 v33, v38, v138
	v_fmac_f32_e32 v34, v39, v139
	v_cvt_pk_bf16_f32 v33, v33, v34
	v_lshlrev_b32_e32 v34, 16, v90
	v_fmac_f32_e32 v34, v28, v132
	v_and_b32_e32 v28, 0xffff0000, v90
	v_fmac_f32_e32 v28, v29, v133
	v_cvt_pk_bf16_f32 v34, v34, v28
	v_lshlrev_b32_e32 v28, 16, v91
	v_fmac_f32_e32 v28, v30, v134
	v_lshlrev_b32_e32 v30, 16, v92
	v_and_b32_e32 v29, 0xffff0000, v91
	v_fmac_f32_e32 v30, v24, v128
	v_and_b32_e32 v24, 0xffff0000, v92
	v_fmac_f32_e32 v29, v31, v135
	v_fmac_f32_e32 v24, v25, v129
	v_lshlrev_b32_e32 v25, 16, v93
	v_cvt_pk_bf16_f32 v35, v28, v29
	v_lshl_add_u64 v[28:29], s[14:15], 0, v[104:105]
	v_fmac_f32_e32 v25, v26, v130
	v_and_b32_e32 v26, 0xffff0000, v93
	v_lshl_add_u64 v[28:29], v[28:29], 0, v[186:187]
	v_fmac_f32_e32 v26, v27, v131
	flat_store_dwordx4 v[28:29], v[32:35]
	v_cvt_pk_bf16_f32 v24, v30, v24
	v_cvt_pk_bf16_f32 v25, v25, v26
	v_lshlrev_b32_e32 v26, 16, v94
	v_fmac_f32_e32 v26, v16, v124
	v_and_b32_e32 v16, 0xffff0000, v94
	v_fmac_f32_e32 v16, v17, v125
	v_cvt_pk_bf16_f32 v26, v26, v16
	v_lshlrev_b32_e32 v16, 16, v95
	v_and_b32_e32 v17, 0xffff0000, v95
	v_fmac_f32_e32 v16, v18, v126
	v_fmac_f32_e32 v17, v19, v127
	v_cvt_pk_bf16_f32 v27, v16, v17
	v_lshlrev_b32_e32 v16, 16, v96
	v_and_b32_e32 v17, 0xffff0000, v96
	v_fmac_f32_e32 v16, v20, v136
	v_fmac_f32_e32 v17, v21, v137
	flat_store_dwordx4 v[28:29], v[24:27] offset:256
	v_cvt_pk_bf16_f32 v16, v16, v17
	v_lshlrev_b32_e32 v17, 16, v97
	v_and_b32_e32 v18, 0xffff0000, v97
	v_fmac_f32_e32 v17, v22, v138
	v_fmac_f32_e32 v18, v23, v139
	v_cvt_pk_bf16_f32 v17, v17, v18
	v_lshlrev_b32_e32 v18, 16, v98
	v_fmac_f32_e32 v18, v12, v132
	v_and_b32_e32 v12, 0xffff0000, v98
	v_fmac_f32_e32 v12, v13, v133
	v_cvt_pk_bf16_f32 v18, v18, v12
	v_lshlrev_b32_e32 v12, 16, v99
	v_fmac_f32_e32 v12, v14, v134
	v_lshlrev_b32_e32 v14, 16, v68
	v_and_b32_e32 v13, 0xffff0000, v99
	v_fmac_f32_e32 v14, v8, v128
	v_and_b32_e32 v8, 0xffff0000, v68
	v_fmac_f32_e32 v13, v15, v135
	v_fmac_f32_e32 v8, v9, v129
	v_lshlrev_b32_e32 v9, 16, v69
	v_cvt_pk_bf16_f32 v19, v12, v13
	v_lshl_add_u64 v[12:13], s[14:15], 0, v[106:107]
	v_fmac_f32_e32 v9, v10, v130
	v_and_b32_e32 v10, 0xffff0000, v69
	v_lshl_add_u64 v[12:13], v[12:13], 0, v[186:187]
	v_fmac_f32_e32 v10, v11, v131
	flat_store_dwordx4 v[12:13], v[16:19]
	v_cvt_pk_bf16_f32 v8, v14, v8
	v_cvt_pk_bf16_f32 v9, v9, v10
	v_lshlrev_b32_e32 v10, 16, v70
	v_fmac_f32_e32 v10, v4, v124
	v_and_b32_e32 v4, 0xffff0000, v70
	v_fmac_f32_e32 v4, v5, v125
	v_cvt_pk_bf16_f32 v10, v10, v4
	v_lshlrev_b32_e32 v4, 16, v71
	v_and_b32_e32 v5, 0xffff0000, v71
	v_fmac_f32_e32 v4, v6, v126
	v_fmac_f32_e32 v5, v7, v127
	v_cvt_pk_bf16_f32 v11, v4, v5
	flat_store_dwordx4 v[12:13], v[8:11] offset:256
	s_cbranch_vccz .LBB0_2227
	s_waitcnt vmcnt(0)
	s_cmpk_gt_u32 s7, 0xff
	s_cbranch_scc1 .LBB0_2242
	s_barrier
